# in-proj K-loops (even/odd, both operand orders) restructured like gate/up: DMA interleaved with MFMAs, SALU m0
# baseline (speedup 1.0000x reference)
; template <bool VT>
; DI int gemm_kloop(const bf16_t* Ag, size_t lda, const bf16_t* Bg, size_t ldb, int nk, bf16_t* ring, f32x16 (&acc)[4][2], int tid, int wm, int wn,
;                   int r, int h, int st0, bool pre, const bf16_t* AgN, const bf16_t* BgN) {
;   const int wid = tid >> 6, lane = tid & 63;
;   const unsigned base = (unsigned)(unsigned long long)ring;
;   const int q = (r >> 2) & 3;
;   const unsigned rA = base + (unsigned)(wm * 128 + r) * 64u, rB = base + (unsigned)STG_A * 2u + (unsigned)(wn * 64 + r) * 64u;
;   const unsigned oA0 = rA + (unsigned)((h ^ q) & 3) * 16u, oA1 = rA + (unsigned)(((2 + h) ^ q) & 3) * 16u;
;   const unsigned oB0 = rB + (unsigned)((h ^ q) & 3) * 16u, oB1 = rB + (unsigned)(((2 + h) ^ q) & 3) * 16u;
;   int st = st0;
;     ...
;   const bf16_t* Ag = A + (size_t)m0 * lda;
;   const bf16_t* Bg = Bt + (size_t)n0 * ldb;
;   if (ssq) {
;     const f32x4* sp = (const f32x4*)(ssq + (size_t)(m0 + tid) * 16);
;     const f32x4 a = sp[0], b = sp[1], c = sp[2], d = sp[3];
;     const float tot = ((a.x + a.y) + (a.z + a.w)) + ((b.x + b.y) + (b.z + b.w)) + ((c.x + c.y) + (c.z + c.w)) + ((d.x + d.y) + (d.z + d.w));
;     sR[tid] = rsqrtf(tot * (1.f / DM) + 1e-6f);
;   }
;   __syncthreads();
;   f32x16 acc[4][2];
; #pragma unroll
;   for (int a = 0; a < 4; ++a)
; #pragma unroll
;     for (int b = 0; b < 2; ++b)
; #pragma unroll
;       for (int i = 0; i < 16; ++i) acc[a][b][i] = 0.f;
;   const bool vt = epi.vtype(n0 + wn * 64);
;   int st_last = 0;
.LBB0_199:
	v_lshlrev_b64 v[138:139], 1, v[32:33]
	s_add_u32 s24, s34, s41
	v_lshlrev_b32_e32 v166, 10, v0
	v_lshlrev_b32_e32 v165, 10, v1
	v_lshl_add_u64 v[0:1], v[132:133], 1, v[138:139]
	s_addc_u32 s25, s35, s42
	v_lshl_add_u64 v[2:3], v[130:131], 1, v[138:139]
	v_lshl_add_u64 v[140:141], s[24:25], 0, v[0:1]
	v_lshl_add_u64 v[142:143], s[24:25], 0, v[2:3]
	s_add_i32 s24, s39, s43
	s_lshl_b32 s24, s24, 11
	s_or_b32 s44, s24, s40
	v_lshlrev_b64 v[4:5], 1, v[136:137]
	v_mad_i64_i32 v[4:5], s[24:25], s44, v211, v[4:5]
	v_lshl_add_u64 v[4:5], v[4:5], 0, v[138:139]
	v_lshl_add_u64 v[144:145], s[6:7], 0, v[4:5]
	v_lshlrev_b64 v[4:5], 1, v[134:135]
	v_mad_i64_i32 v[0:1], s[24:25], s44, v211, v[0:1]
	v_mad_i64_i32 v[4:5], s[24:25], s44, v211, v[4:5]
	v_lshl_add_u64 v[148:149], s[6:7], 0, v[0:1]
	v_mad_i64_i32 v[0:1], s[24:25], s44, v211, v[2:3]
	v_lshl_add_u64 v[4:5], v[4:5], 0, v[138:139]
	v_lshl_add_u64 v[150:151], s[6:7], 0, v[0:1]
	v_mov_b32_e32 v0, 0
	v_lshl_add_u64 v[146:147], s[6:7], 0, v[4:5]
	s_mov_b64 s[24:25], 0
	v_mov_b32_e32 v1, v0
	v_mov_b32_e32 v2, v0
	v_mov_b32_e32 v3, v0
	v_mov_b32_e32 v4, v0
	v_mov_b32_e32 v5, v0
	v_mov_b32_e32 v6, v0
	v_mov_b32_e32 v7, v0
	v_mov_b32_e32 v8, v0
	v_mov_b32_e32 v9, v0
	v_mov_b32_e32 v10, v0
	v_mov_b32_e32 v11, v0
	v_mov_b32_e32 v12, v0
	v_mov_b32_e32 v13, v0
	v_mov_b32_e32 v14, v0
	v_mov_b32_e32 v15, v0
	v_mov_b32_e32 v16, v0
	v_mov_b32_e32 v17, v0
	v_mov_b32_e32 v18, v0
	v_mov_b32_e32 v19, v0
	v_mov_b32_e32 v20, v0
	v_mov_b32_e32 v21, v0
	v_mov_b32_e32 v22, v0
	v_mov_b32_e32 v23, v0
	v_mov_b32_e32 v24, v0
	v_mov_b32_e32 v25, v0
	v_mov_b32_e32 v26, v0
	v_mov_b32_e32 v27, v0
	v_mov_b32_e32 v28, v0
	v_mov_b32_e32 v29, v0
	v_mov_b32_e32 v30, v0
	v_mov_b32_e32 v31, v0
	v_mov_b32_e32 v34, v0
	v_mov_b32_e32 v35, v0
	v_mov_b32_e32 v36, v0
	v_mov_b32_e32 v37, v0
	v_mov_b32_e32 v38, v0
	v_mov_b32_e32 v39, v0
	v_mov_b32_e32 v40, v0
	v_mov_b32_e32 v41, v0
	v_mov_b32_e32 v42, v0
	v_mov_b32_e32 v43, v0
	v_mov_b32_e32 v44, v0
	v_mov_b32_e32 v45, v0
	v_mov_b32_e32 v46, v0
	v_mov_b32_e32 v47, v0
	v_mov_b32_e32 v48, v0
	v_mov_b32_e32 v49, v0
	v_mov_b32_e32 v50, v0
	v_mov_b32_e32 v51, v0
	v_mov_b32_e32 v52, v0
	v_mov_b32_e32 v53, v0
	v_mov_b32_e32 v54, v0
	v_mov_b32_e32 v55, v0
	v_mov_b32_e32 v56, v0
	v_mov_b32_e32 v57, v0
	v_mov_b32_e32 v58, v0
	v_mov_b32_e32 v59, v0
	v_mov_b32_e32 v60, v0
	v_mov_b32_e32 v61, v0
	v_mov_b32_e32 v62, v0
	v_mov_b32_e32 v63, v0
	v_mov_b32_e32 v64, v0
	v_mov_b32_e32 v65, v0
	v_mov_b32_e32 v66, v0
	v_mov_b32_e32 v67, v0
	v_mov_b32_e32 v68, v0
	v_mov_b32_e32 v69, v0
	v_mov_b32_e32 v70, v0
	v_mov_b32_e32 v71, v0
	v_mov_b32_e32 v72, v0
	v_mov_b32_e32 v73, v0
	v_mov_b32_e32 v74, v0
	v_mov_b32_e32 v75, v0
	v_mov_b32_e32 v76, v0
	v_mov_b32_e32 v77, v0
	v_mov_b32_e32 v78, v0
	v_mov_b32_e32 v79, v0
	v_mov_b32_e32 v80, v0
	v_mov_b32_e32 v81, v0
	v_mov_b32_e32 v82, v0
	v_mov_b32_e32 v83, v0
	v_mov_b32_e32 v84, v0
	v_mov_b32_e32 v85, v0
	v_mov_b32_e32 v86, v0
	v_mov_b32_e32 v87, v0
	v_mov_b32_e32 v88, v0
	v_mov_b32_e32 v89, v0
	v_mov_b32_e32 v90, v0
	v_mov_b32_e32 v91, v0
	v_mov_b32_e32 v92, v0
	v_mov_b32_e32 v93, v0
	v_mov_b32_e32 v94, v0
	v_mov_b32_e32 v95, v0
	v_mov_b32_e32 v96, v0
	v_mov_b32_e32 v97, v0
	v_mov_b32_e32 v98, v0
	v_mov_b32_e32 v99, v0
	v_mov_b32_e32 v100, v0
	v_mov_b32_e32 v101, v0
	v_mov_b32_e32 v102, v0
	v_mov_b32_e32 v103, v0
	v_mov_b32_e32 v104, v0
	v_mov_b32_e32 v105, v0
	v_mov_b32_e32 v106, v0
	v_mov_b32_e32 v107, v0
	v_mov_b32_e32 v108, v0
	v_mov_b32_e32 v109, v0
	v_mov_b32_e32 v110, v0
	v_mov_b32_e32 v111, v0
	v_mov_b32_e32 v112, v0
	v_mov_b32_e32 v113, v0
	v_mov_b32_e32 v114, v0
	v_mov_b32_e32 v115, v0
	v_mov_b32_e32 v116, v0
	v_mov_b32_e32 v117, v0
	v_mov_b32_e32 v118, v0
	v_mov_b32_e32 v119, v0
	v_mov_b32_e32 v120, v0
	v_mov_b32_e32 v121, v0
	v_mov_b32_e32 v122, v0
	v_mov_b32_e32 v123, v0
	v_mov_b32_e32 v124, v0
	v_mov_b32_e32 v125, v0
	v_mov_b32_e32 v126, v0
	v_mov_b32_e32 v127, v0
	v_mov_b32_e32 v128, v0
	v_mov_b32_e32 v129, v0
	v_readfirstlane_b32 s99, v163
	s_lshl_b32 s99, s99, 1
.LBB0_200:
	v_mul_lo_u32 v32, v162, s95
	v_readfirstlane_b32 s44, v162
	v_lshl_add_u64 v[168:169], v[150:151], 0, s[24:25]
	s_mul_i32 s98, s44, 0x3000
	s_addk_i32 s98, 0xd000
	s_cmp_lg_u32 s44, 0
	s_cselect_b32 s98, s98, 0x6000
	s_lshl_b32 s98, s98, 1
	s_add_u32 s98, s98, s99
	s_mul_i32 s44, s44, 0x6000
	v_add_u32_e32 v176, s44, v160
	v_add_u32_e32 v167, s44, v158
	v_add_u32_e32 v32, s44, v161
	v_add_u32_e32 v239, s44, v159
	s_mov_b32 m0, s98
	s_waitcnt vmcnt(6)
	s_barrier
; template <bool VT>
; DI void g_compute_asm(unsigned aA0, unsigned aA1, unsigned aB0, unsigned aB1, f32x16 (&acc)[4][2]) {
;   bf16x8 a0[4], a1[4], b0[2], b1[2];
;   DSR(b0[0], aB0, 0); DSR(b0[1], aB0, 2048);
;   DSR(a0[0], aA0, 0); DSR(a0[1], aA0, 2048); DSR(a0[2], aA0, 4096); DSR(a0[3], aA0, 6144);
;   DSR(b1[0], aB1, 0); DSR(b1[1], aB1, 2048);
;   DSR(a1[0], aA1, 0); DSR(a1[1], aA1, 2048); DSR(a1[2], aA1, 4096); DSR(a1[3], aA1, 6144);
;   asm volatile("s_waitcnt lgkmcnt(6)" : "+v"(b0[0]), "+v"(b0[1]), "+v"(a0[0]), "+v"(a0[1]), "+v"(a0[2]), "+v"(a0[3]));
; #pragma unroll
;   for (int mi = 0; mi < 4; ++mi)
; #pragma unroll
;     for (int ni = 0; ni < 2; ++ni) {
;       if (VT) acc[mi][ni] = MFMA(a0[mi], b0[ni], acc[mi][ni]);
;       else acc[mi][ni] = MFMA(b0[ni], a0[mi], acc[mi][ni]);
;     }
;   __builtin_amdgcn_sched_barrier(0);
;   asm volatile("s_waitcnt lgkmcnt(0)" : "+v"(b1[0]), "+v"(b1[1]), "+v"(a1[0]), "+v"(a1[1]), "+v"(a1[2]), "+v"(a1[3]));
; #pragma unroll
;   for (int mi = 0; mi < 4; ++mi)
; #pragma unroll
;     for (int ni = 0; ni < 2; ++ni) {
;       if (VT) acc[mi][ni] = MFMA(a1[mi], b1[ni], acc[mi][ni]);
;       else acc[mi][ni] = MFMA(b1[ni], a1[mi], acc[mi][ni]);
;     }
; }
; template <bool VT>
; DI int gemm_kloop(const bf16_t* Ag, size_t lda, const bf16_t* Bg, size_t ldb, int nk, bf16_t* ring, f32x16 (&acc)[4][2], int tid, int wm, int wn,
;                   int r, int h, int st0, bool pre, const bf16_t* AgN, const bf16_t* BgN) {
;     ...
;   for (int kt = 0; kt < nk - 1; ++kt) {
;     asm volatile("s_waitcnt vmcnt(6)" ::: "memory");
;     __builtin_amdgcn_s_barrier();
;     if (kt + 2 < nk) dma_issue(Ag, lda, Bg, ldb, kt + 2, ring + (st == 0 ? 2 : st - 1) * STG, wid, lane);
;     const unsigned so = (unsigned)st * (unsigned)(STG * 2);
;     g_compute_asm<VT>(oA0 + so, oA1 + so, oB0 + so, oB1 + so, acc);
;     st = st == 2 ? 0 : st + 1;
;   }
;   asm volatile("s_waitcnt vmcnt(0)" ::: "memory");
;   __builtin_amdgcn_s_barrier();
;   if (AgN) {
;     const int s1 = st == 2 ? 0 : st + 1, s2 = s1 == 2 ? 0 : s1 + 1;
;     dma_issue(AgN, lda, BgN, ldb, 0, ring + s1 * STG, wid, lane);
;     dma_issue(AgN, lda, BgN, ldb, 1, ring + s2 * STG, wid, lane);
;   }
;   {
;     const unsigned so = (unsigned)st * (unsigned)(STG * 2);
;     g_compute_asm<VT>(oA0 + so, oA1 + so, oB0 + so, oB1 + so, acc);
	global_load_lds_dwordx4 v[168:169], off
	ds_read_b128 v[168:171], v176 offset:0
	ds_read_b128 v[172:175], v176 offset:2048
	ds_read_b128 v[176:179], v167 offset:0
	ds_read_b128 v[180:183], v167 offset:2048
	ds_read_b128 v[184:187], v167 offset:4096
	ds_read_b128 v[188:191], v167 offset:6144
	ds_read_b128 v[192:195], v32 offset:0
	ds_read_b128 v[196:199], v32 offset:2048
	ds_read_b128 v[200:203], v239 offset:0
	ds_read_b128 v[204:207], v239 offset:2048
	ds_read_b128 v[244:247], v239 offset:4096
	ds_read_b128 v[248:251], v239 offset:6144
	s_waitcnt lgkmcnt(9)
	v_mfma_f32_32x32x16_bf16 v[114:129], v[168:171], v[176:179], v[114:129]
	v_mfma_f32_32x32x16_bf16 v[98:113], v[172:175], v[176:179], v[98:113]
	s_add_u32 m0, s98, 0x1000
	v_lshl_add_u64 v[176:177], v[148:149], 0, s[24:25]
	global_load_lds_dwordx4 v[176:177], off
	s_waitcnt lgkmcnt(8)
	v_mfma_f32_32x32x16_bf16 v[82:97], v[168:171], v[180:183], v[82:97]
	v_mfma_f32_32x32x16_bf16 v[66:81], v[172:175], v[180:183], v[66:81]
	s_add_u32 m0, s98, 0x2000
	v_lshl_add_u64 v[176:177], v[146:147], 0, s[24:25]
	global_load_lds_dwordx4 v[176:177], off
	s_waitcnt lgkmcnt(7)
	v_mfma_f32_32x32x16_bf16 v[50:65], v[168:171], v[184:187], v[50:65]
	v_mfma_f32_32x32x16_bf16 v[34:49], v[172:175], v[184:187], v[34:49]
	s_add_u32 m0, s98, 0x3000
	v_lshl_add_u64 v[176:177], v[144:145], 0, s[24:25]
	global_load_lds_dwordx4 v[176:177], off
	s_waitcnt lgkmcnt(6)
	v_mfma_f32_32x32x16_bf16 v[16:31], v[168:171], v[188:191], v[16:31]
	v_mfma_f32_32x32x16_bf16 v[0:15], v[172:175], v[188:191], v[0:15]
	s_add_u32 m0, s98, 0x4000
	v_lshl_add_u64 v[176:177], v[142:143], 0, s[24:25]
	global_load_lds_dwordx4 v[176:177], off
	s_waitcnt lgkmcnt(3)
	v_mfma_f32_32x32x16_bf16 v[114:129], v[192:195], v[200:203], v[114:129]
	v_mfma_f32_32x32x16_bf16 v[98:113], v[196:199], v[200:203], v[98:113]
	s_add_u32 m0, s98, 0x5000
	v_lshl_add_u64 v[176:177], v[140:141], 0, s[24:25]
	global_load_lds_dwordx4 v[176:177], off
	s_add_u32 s24, s24, 64
	v_add_u32_e32 v32, 1, v162
	v_cmp_ne_u32_e32 vcc, 2, v162
	s_addc_u32 s25, s25, 0
	s_cmpk_eq_i32 s24, 0x780
	v_cndmask_b32_e32 v162, 0, v32, vcc
	s_waitcnt lgkmcnt(2)
	v_mfma_f32_32x32x16_bf16 v[82:97], v[192:195], v[204:207], v[82:97]
	v_mfma_f32_32x32x16_bf16 v[66:81], v[196:199], v[204:207], v[66:81]
	s_waitcnt lgkmcnt(1)
	v_mfma_f32_32x32x16_bf16 v[50:65], v[192:195], v[244:247], v[50:65]
	v_mfma_f32_32x32x16_bf16 v[34:49], v[196:199], v[244:247], v[34:49]
	s_waitcnt lgkmcnt(0)
	v_mfma_f32_32x32x16_bf16 v[16:31], v[192:195], v[248:251], v[16:31]
	v_mfma_f32_32x32x16_bf16 v[0:15], v[196:199], v[248:251], v[0:15]
	s_cbranch_scc0 .LBB0_200
	v_mul_lo_u32 v32, v162, s84
	v_add_u32_e32 v148, v32, v160
	s_waitcnt vmcnt(6)
	s_barrier
	v_add_u32_e32 v167, v32, v158
	ds_read_b128 v[140:143], v148 offset:0
	ds_read_b128 v[144:147], v148 offset:2048
	ds_read_b128 v[148:151], v167 offset:0
	ds_read_b128 v[168:171], v167 offset:2048
	ds_read_b128 v[172:175], v167 offset:4096
	ds_read_b128 v[176:179], v167 offset:6144
	v_add_u32_e32 v204, v32, v159
	v_add_u32_e32 v32, v32, v161
	ds_read_b128 v[180:183], v32 offset:0
	ds_read_b128 v[184:187], v32 offset:2048
	ds_read_b128 v[188:191], v204 offset:0
	ds_read_b128 v[192:195], v204 offset:2048
	ds_read_b128 v[196:199], v204 offset:4096
	ds_read_b128 v[200:203], v204 offset:6144
	s_waitcnt lgkmcnt(6)
	s_nop 0
	v_mfma_f32_32x32x16_bf16 v[114:129], v[140:143], v[148:151], v[114:129]
	v_mfma_f32_32x32x16_bf16 v[98:113], v[144:147], v[148:151], v[98:113]
	v_mfma_f32_32x32x16_bf16 v[82:97], v[140:143], v[168:171], v[82:97]
	v_mfma_f32_32x32x16_bf16 v[66:81], v[144:147], v[168:171], v[66:81]
	v_mfma_f32_32x32x16_bf16 v[50:65], v[140:143], v[172:175], v[50:65]
	v_mfma_f32_32x32x16_bf16 v[34:49], v[144:147], v[172:175], v[34:49]
	v_mfma_f32_32x32x16_bf16 v[16:31], v[140:143], v[176:179], v[16:31]
	v_mfma_f32_32x32x16_bf16 v[0:15], v[144:147], v[176:179], v[0:15]
	s_waitcnt lgkmcnt(0)
	s_waitcnt vmcnt(0)
	v_add_u32_e32 v32, 1, v162
	v_mfma_f32_32x32x16_bf16 v[114:129], v[180:183], v[188:191], v[114:129]
	v_cmp_ne_u32_e32 vcc, 2, v162
	s_cmp_lg_u64 s[12:13], 0
	s_barrier
; DI void dma_issue(const bf16_t* Ag, size_t lda, const bf16_t* Bg, size_t ldb, int kt, bf16_t* stage, int wid, int lane) {
;   const int rl = lane >> 2, c = (lane & 3) ^ ((lane >> 4) & 3);
; #pragma unroll
;   for (int i = 0; i < 4; ++i) {
;     const int j = wid + 4 * i;
;     __builtin_amdgcn_global_load_lds((const unsigned*)(Ag + (size_t)(16 * j + rl) * lda + kt * 32 + c * 8), (unsigned*)(stage + j * 512), 16, 0, 0);
;   }
; #pragma unroll
;   for (int i = 0; i < 2; ++i) {
;     const int j = wid + 4 * i;
;     __builtin_amdgcn_global_load_lds((const unsigned*)(Bg + (size_t)(16 * j + rl) * ldb + kt * 32 + c * 8), (unsigned*)(stage + STG_A + j * 512), 16, 0, 0);
;   }
; }
; template <bool VT>
; DI int gemm_kloop(const bf16_t* Ag, size_t lda, const bf16_t* Bg, size_t ldb, int nk, bf16_t* ring, f32x16 (&acc)[4][2], int tid, int wm, int wn,
;                   int r, int h, int st0, bool pre, const bf16_t* AgN, const bf16_t* BgN) {
;     ...
;   if (AgN) {
;     const int s1 = st == 2 ? 0 : st + 1, s2 = s1 == 2 ? 0 : s1 + 1;
;     dma_issue(AgN, lda, BgN, ldb, 0, ring + s1 * STG, wid, lane);
;     dma_issue(AgN, lda, BgN, ldb, 1, ring + s2 * STG, wid, lane);
;   }
;   {
;     const unsigned so = (unsigned)st * (unsigned)(STG * 2);
;     g_compute_asm<VT>(oA0 + so, oA1 + so, oB0 + so, oB1 + so, acc);
	v_cndmask_b32_e32 v140, 0, v32, vcc
	v_mfma_f32_32x32x16_bf16 v[98:113], v[184:187], v[188:191], v[98:113]
	v_mfma_f32_32x32x16_bf16 v[82:97], v[180:183], v[192:195], v[82:97]
	v_mfma_f32_32x32x16_bf16 v[66:81], v[184:187], v[192:195], v[66:81]
	v_mfma_f32_32x32x16_bf16 v[50:65], v[180:183], v[196:199], v[50:65]
	v_mfma_f32_32x32x16_bf16 v[34:49], v[184:187], v[196:199], v[34:49]
	v_mfma_f32_32x32x16_bf16 v[16:31], v[180:183], v[200:203], v[16:31]
	v_mfma_f32_32x32x16_bf16 v[0:15], v[184:187], v[200:203], v[0:15]
	s_cbranch_scc0 .LBB0_203
	v_add_u32_e32 v32, 1, v140
	v_cmp_ne_u32_e32 vcc, 2, v140
	v_lshlrev_b32_e32 v149, 1, v163
	v_lshlrev_b32_e32 v151, 1, v164
	v_cndmask_b32_e32 v32, 0, v32, vcc
	v_mul_lo_u32 v141, v32, s95
	v_lshlrev_b32_e32 v148, 1, v141
	v_add_u32_e32 v150, v148, v149
	v_lshl_add_u64 v[142:143], s[12:13], 0, v[138:139]
	v_lshlrev_b64 v[130:131], 1, v[130:131]
	v_readfirstlane_b32 s24, v150
	v_add_u32_e32 v162, v148, v151
	v_lshl_add_u64 v[144:145], v[142:143], 0, v[130:131]
	s_mov_b32 m0, s24
	v_lshlrev_b64 v[132:133], 1, v[132:133]
	v_readfirstlane_b32 s24, v162
	v_add_u32_e32 v163, v148, v166
	global_load_lds_dwordx4 v[144:145], off
	v_lshl_add_u64 v[146:147], v[142:143], 0, v[132:133]
	s_mov_b32 m0, s24
	v_lshl_add_u64 v[134:135], v[134:135], 1, v[142:143]
	v_readfirstlane_b32 s24, v163
	v_lshl_add_u64 v[136:137], v[136:137], 1, v[142:143]
	v_add_u32_e32 v142, v148, v165
	global_load_lds_dwordx4 v[146:147], off
	s_mov_b32 m0, s24
	v_readfirstlane_b32 s24, v142
	v_lshl_add_u64 v[138:139], s[14:15], 0, v[138:139]
	v_add_u32_e32 v142, 0x4000, v150
	global_load_lds_dwordx4 v[134:135], off
	s_mov_b32 m0, s24
	v_lshl_add_u64 v[130:131], v[138:139], 0, v[130:131]
	v_readfirstlane_b32 s24, v142
	v_lshl_add_u64 v[132:133], v[138:139], 0, v[132:133]
	v_add_u32_e32 v138, 0x4000, v162
	global_load_lds_dwordx4 v[136:137], off
	s_mov_b32 m0, s24
	v_readfirstlane_b32 s24, v138
	v_add_u32_e32 v138, 0x3000, v141
	v_cmp_ne_u32_e32 vcc, 2, v32
	global_load_lds_dwordx4 v[130:131], off
	s_nop 0
	v_cndmask_b32_e32 v32, 0, v138, vcc
	v_lshlrev_b32_e32 v32, 1, v32
	v_add_u32_e32 v141, v32, v149
	s_mov_b32 m0, s24
	v_readfirstlane_b32 s24, v141
	v_add_u32_e32 v142, v32, v151
	global_load_lds_dwordx4 v[132:133], off
	v_lshl_add_u64 v[138:139], v[144:145], 0, 64
	s_mov_b32 m0, s24
	v_readfirstlane_b32 s24, v142
	global_load_lds_dwordx4 v[138:139], off
	v_lshl_add_u64 v[138:139], v[146:147], 0, 64
	s_mov_b32 m0, s24
	v_lshl_add_u64 v[134:135], v[134:135], 0, 64
	global_load_lds_dwordx4 v[138:139], off
	v_add_u32_e32 v138, v32, v166
	v_add_u32_e32 v32, v32, v165
	v_readfirstlane_b32 s24, v138
	s_mov_b32 m0, s24
	v_readfirstlane_b32 s24, v32
	v_add_u32_e32 v32, 0x4000, v141
	global_load_lds_dwordx4 v[134:135], off
	v_lshl_add_u64 v[134:135], v[136:137], 0, 64
	s_mov_b32 m0, s24
	v_readfirstlane_b32 s24, v32
	v_add_u32_e32 v32, 0x4000, v142
	global_load_lds_dwordx4 v[134:135], off
	v_lshl_add_u64 v[130:131], v[130:131], 0, 64
	s_mov_b32 m0, s24
	v_readfirstlane_b32 s24, v32
	global_load_lds_dwordx4 v[130:131], off
	v_lshl_add_u64 v[130:131], v[132:133], 0, 64
	s_mov_b32 m0, s24
	s_nop 0
	global_load_lds_dwordx4 v[130:131], off

; template <bool VT>
; DI int gemm_kloop(const bf16_t* Ag, size_t lda, const bf16_t* Bg, size_t ldb, int nk, bf16_t* ring, f32x16 (&acc)[4][2], int tid, int wm, int wn,
;                   int r, int h, int st0, bool pre, const bf16_t* AgN, const bf16_t* BgN) {
;   const int wid = tid >> 6, lane = tid & 63;
;   const unsigned base = (unsigned)(unsigned long long)ring;
;   const int q = (r >> 2) & 3;
;   const unsigned rA = base + (unsigned)(wm * 128 + r) * 64u, rB = base + (unsigned)STG_A * 2u + (unsigned)(wn * 64 + r) * 64u;
;   const unsigned oA0 = rA + (unsigned)((h ^ q) & 3) * 16u, oA1 = rA + (unsigned)(((2 + h) ^ q) & 3) * 16u;
;   const unsigned oB0 = rB + (unsigned)((h ^ q) & 3) * 16u, oB1 = rB + (unsigned)(((2 + h) ^ q) & 3) * 16u;
;   int st = st0;
;     ...
;   const bf16_t* Ag = A + (size_t)m0 * lda;
;   const bf16_t* Bg = Bt + (size_t)n0 * ldb;
;   if (ssq) {
;     const f32x4* sp = (const f32x4*)(ssq + (size_t)(m0 + tid) * 16);
;     const f32x4 a = sp[0], b = sp[1], c = sp[2], d = sp[3];
;     const float tot = ((a.x + a.y) + (a.z + a.w)) + ((b.x + b.y) + (b.z + b.w)) + ((c.x + c.y) + (c.z + c.w)) + ((d.x + d.y) + (d.z + d.w));
;     sR[tid] = rsqrtf(tot * (1.f / DM) + 1e-6f);
;   }
;   __syncthreads();
;   f32x16 acc[4][2];
; #pragma unroll
;   for (int a = 0; a < 4; ++a)
; #pragma unroll
;     for (int b = 0; b < 2; ++b)
; #pragma unroll
;       for (int i = 0; i < 16; ++i) acc[a][b][i] = 0.f;
;   const bool vt = epi.vtype(n0 + wn * 64);
;   int st_last = 0;
.LBB0_209:
	v_lshlrev_b64 v[138:139], 1, v[32:33]
	s_add_u32 s16, s34, s41
	v_lshl_add_u64 v[0:1], v[132:133], 1, v[138:139]
	s_addc_u32 s17, s35, s42
	v_lshl_add_u64 v[2:3], v[130:131], 1, v[138:139]
	s_add_i32 s39, s39, s43
	v_lshl_add_u64 v[140:141], s[16:17], 0, v[0:1]
	v_lshl_add_u64 v[142:143], s[16:17], 0, v[2:3]
	s_lshl_b32 s16, s39, 11
	s_or_b32 s18, s16, s40
	v_lshlrev_b64 v[4:5], 1, v[136:137]
	v_mad_i64_i32 v[4:5], s[16:17], s18, v211, v[4:5]
	v_lshl_add_u64 v[4:5], v[4:5], 0, v[138:139]
	v_lshl_add_u64 v[144:145], s[6:7], 0, v[4:5]
	v_lshlrev_b64 v[4:5], 1, v[134:135]
	v_mad_i64_i32 v[0:1], s[16:17], s18, v211, v[0:1]
	v_mad_i64_i32 v[4:5], s[16:17], s18, v211, v[4:5]
	v_lshl_add_u64 v[148:149], s[6:7], 0, v[0:1]
	v_mad_i64_i32 v[0:1], s[16:17], s18, v211, v[2:3]
	v_lshl_add_u64 v[4:5], v[4:5], 0, v[138:139]
	v_lshl_add_u64 v[150:151], s[6:7], 0, v[0:1]
	v_mov_b32_e32 v0, 0
	v_lshlrev_b32_e32 v166, 10, v6
	v_lshlrev_b32_e32 v165, 10, v7
	v_lshl_add_u64 v[146:147], s[6:7], 0, v[4:5]
	s_mov_b64 s[16:17], 0
	v_mov_b32_e32 v1, v0
	v_mov_b32_e32 v2, v0
	v_mov_b32_e32 v3, v0
	v_mov_b32_e32 v4, v0
	v_mov_b32_e32 v5, v0
	v_mov_b32_e32 v6, v0
	v_mov_b32_e32 v7, v0
	v_mov_b32_e32 v8, v0
	v_mov_b32_e32 v9, v0
	v_mov_b32_e32 v10, v0
	v_mov_b32_e32 v11, v0
	v_mov_b32_e32 v12, v0
	v_mov_b32_e32 v13, v0
	v_mov_b32_e32 v14, v0
	v_mov_b32_e32 v15, v0
	v_mov_b32_e32 v16, v0
	v_mov_b32_e32 v17, v0
	v_mov_b32_e32 v18, v0
	v_mov_b32_e32 v19, v0
	v_mov_b32_e32 v20, v0
	v_mov_b32_e32 v21, v0
	v_mov_b32_e32 v22, v0
	v_mov_b32_e32 v23, v0
	v_mov_b32_e32 v24, v0
	v_mov_b32_e32 v25, v0
	v_mov_b32_e32 v26, v0
	v_mov_b32_e32 v27, v0
	v_mov_b32_e32 v28, v0
	v_mov_b32_e32 v29, v0
	v_mov_b32_e32 v30, v0
	v_mov_b32_e32 v31, v0
	v_mov_b32_e32 v34, v0
	v_mov_b32_e32 v35, v0
	v_mov_b32_e32 v36, v0
	v_mov_b32_e32 v37, v0
	v_mov_b32_e32 v38, v0
	v_mov_b32_e32 v39, v0
	v_mov_b32_e32 v40, v0
	v_mov_b32_e32 v41, v0
	v_mov_b32_e32 v42, v0
	v_mov_b32_e32 v43, v0
	v_mov_b32_e32 v44, v0
	v_mov_b32_e32 v45, v0
	v_mov_b32_e32 v46, v0
	v_mov_b32_e32 v47, v0
	v_mov_b32_e32 v48, v0
	v_mov_b32_e32 v49, v0
	v_mov_b32_e32 v50, v0
	v_mov_b32_e32 v51, v0
	v_mov_b32_e32 v52, v0
	v_mov_b32_e32 v53, v0
	v_mov_b32_e32 v54, v0
	v_mov_b32_e32 v55, v0
	v_mov_b32_e32 v56, v0
	v_mov_b32_e32 v57, v0
	v_mov_b32_e32 v58, v0
	v_mov_b32_e32 v59, v0
	v_mov_b32_e32 v60, v0
	v_mov_b32_e32 v61, v0
	v_mov_b32_e32 v62, v0
	v_mov_b32_e32 v63, v0
	v_mov_b32_e32 v64, v0
	v_mov_b32_e32 v65, v0
	v_mov_b32_e32 v66, v0
	v_mov_b32_e32 v67, v0
	v_mov_b32_e32 v68, v0
	v_mov_b32_e32 v69, v0
	v_mov_b32_e32 v70, v0
	v_mov_b32_e32 v71, v0
	v_mov_b32_e32 v72, v0
	v_mov_b32_e32 v73, v0
	v_mov_b32_e32 v74, v0
	v_mov_b32_e32 v75, v0
	v_mov_b32_e32 v76, v0
	v_mov_b32_e32 v77, v0
	v_mov_b32_e32 v78, v0
	v_mov_b32_e32 v79, v0
	v_mov_b32_e32 v80, v0
	v_mov_b32_e32 v81, v0
	v_mov_b32_e32 v82, v0
	v_mov_b32_e32 v83, v0
	v_mov_b32_e32 v84, v0
	v_mov_b32_e32 v85, v0
	v_mov_b32_e32 v86, v0
	v_mov_b32_e32 v87, v0
	v_mov_b32_e32 v88, v0
	v_mov_b32_e32 v89, v0
	v_mov_b32_e32 v90, v0
	v_mov_b32_e32 v91, v0
	v_mov_b32_e32 v92, v0
	v_mov_b32_e32 v93, v0
	v_mov_b32_e32 v94, v0
	v_mov_b32_e32 v95, v0
	v_mov_b32_e32 v96, v0
	v_mov_b32_e32 v97, v0
	v_mov_b32_e32 v98, v0
	v_mov_b32_e32 v99, v0
	v_mov_b32_e32 v100, v0
	v_mov_b32_e32 v101, v0
	v_mov_b32_e32 v102, v0
	v_mov_b32_e32 v103, v0
	v_mov_b32_e32 v104, v0
	v_mov_b32_e32 v105, v0
	v_mov_b32_e32 v106, v0
	v_mov_b32_e32 v107, v0
	v_mov_b32_e32 v108, v0
	v_mov_b32_e32 v109, v0
	v_mov_b32_e32 v110, v0
	v_mov_b32_e32 v111, v0
	v_mov_b32_e32 v112, v0
	v_mov_b32_e32 v113, v0
	v_mov_b32_e32 v114, v0
	v_mov_b32_e32 v115, v0
	v_mov_b32_e32 v116, v0
	v_mov_b32_e32 v117, v0
	v_mov_b32_e32 v118, v0
	v_mov_b32_e32 v119, v0
	v_mov_b32_e32 v120, v0
	v_mov_b32_e32 v121, v0
	v_mov_b32_e32 v122, v0
	v_mov_b32_e32 v123, v0
	v_mov_b32_e32 v124, v0
	v_mov_b32_e32 v125, v0
	v_mov_b32_e32 v126, v0
	v_mov_b32_e32 v127, v0
	v_mov_b32_e32 v128, v0
	v_mov_b32_e32 v129, v0
	v_readfirstlane_b32 s99, v164
	s_lshl_b32 s99, s99, 1
.LBB0_210:
	v_mul_lo_u32 v32, v162, s95
	v_readfirstlane_b32 s18, v162
	v_lshl_add_u64 v[168:169], v[150:151], 0, s[16:17]
	s_mul_i32 s98, s18, 0x3000
	s_addk_i32 s98, 0xd000
	s_cmp_lg_u32 s18, 0
	s_cselect_b32 s98, s98, 0x6000
	s_lshl_b32 s98, s98, 1
	s_add_u32 s98, s98, s99
	s_mul_i32 s18, s18, 0x6000
	v_add_u32_e32 v176, s18, v160
	v_add_u32_e32 v167, s18, v158
	v_add_u32_e32 v32, s18, v161
	v_add_u32_e32 v239, s18, v159
	s_mov_b32 m0, s98
	s_waitcnt vmcnt(6)
	s_barrier
; template <bool VT>
; DI void g_compute_asm(unsigned aA0, unsigned aA1, unsigned aB0, unsigned aB1, f32x16 (&acc)[4][2]) {
;   bf16x8 a0[4], a1[4], b0[2], b1[2];
;   DSR(b0[0], aB0, 0); DSR(b0[1], aB0, 2048);
;   DSR(a0[0], aA0, 0); DSR(a0[1], aA0, 2048); DSR(a0[2], aA0, 4096); DSR(a0[3], aA0, 6144);
;   DSR(b1[0], aB1, 0); DSR(b1[1], aB1, 2048);
;   DSR(a1[0], aA1, 0); DSR(a1[1], aA1, 2048); DSR(a1[2], aA1, 4096); DSR(a1[3], aA1, 6144);
;   asm volatile("s_waitcnt lgkmcnt(6)" : "+v"(b0[0]), "+v"(b0[1]), "+v"(a0[0]), "+v"(a0[1]), "+v"(a0[2]), "+v"(a0[3]));
; #pragma unroll
;   for (int mi = 0; mi < 4; ++mi)
; #pragma unroll
;     for (int ni = 0; ni < 2; ++ni) {
;       if (VT) acc[mi][ni] = MFMA(a0[mi], b0[ni], acc[mi][ni]);
;       else acc[mi][ni] = MFMA(b0[ni], a0[mi], acc[mi][ni]);
;     }
;   __builtin_amdgcn_sched_barrier(0);
;   asm volatile("s_waitcnt lgkmcnt(0)" : "+v"(b1[0]), "+v"(b1[1]), "+v"(a1[0]), "+v"(a1[1]), "+v"(a1[2]), "+v"(a1[3]));
; #pragma unroll
;   for (int mi = 0; mi < 4; ++mi)
; #pragma unroll
;     for (int ni = 0; ni < 2; ++ni) {
;       if (VT) acc[mi][ni] = MFMA(a1[mi], b1[ni], acc[mi][ni]);
;       else acc[mi][ni] = MFMA(b1[ni], a1[mi], acc[mi][ni]);
;     }
; }
; template <bool VT>
; DI int gemm_kloop(const bf16_t* Ag, size_t lda, const bf16_t* Bg, size_t ldb, int nk, bf16_t* ring, f32x16 (&acc)[4][2], int tid, int wm, int wn,
;                   int r, int h, int st0, bool pre, const bf16_t* AgN, const bf16_t* BgN) {
;     ...
;   for (int kt = 0; kt < nk - 1; ++kt) {
;     asm volatile("s_waitcnt vmcnt(6)" ::: "memory");
;     __builtin_amdgcn_s_barrier();
;     if (kt + 2 < nk) dma_issue(Ag, lda, Bg, ldb, kt + 2, ring + (st == 0 ? 2 : st - 1) * STG, wid, lane);
;     const unsigned so = (unsigned)st * (unsigned)(STG * 2);
;     g_compute_asm<VT>(oA0 + so, oA1 + so, oB0 + so, oB1 + so, acc);
;     st = st == 2 ? 0 : st + 1;
;   }
;   asm volatile("s_waitcnt vmcnt(0)" ::: "memory");
;   __builtin_amdgcn_s_barrier();
;   if (AgN) {
;     const int s1 = st == 2 ? 0 : st + 1, s2 = s1 == 2 ? 0 : s1 + 1;
;     dma_issue(AgN, lda, BgN, ldb, 0, ring + s1 * STG, wid, lane);
;     dma_issue(AgN, lda, BgN, ldb, 1, ring + s2 * STG, wid, lane);
;   }
;   {
;     const unsigned so = (unsigned)st * (unsigned)(STG * 2);
;     g_compute_asm<VT>(oA0 + so, oA1 + so, oB0 + so, oB1 + so, acc);
	global_load_lds_dwordx4 v[168:169], off
	ds_read_b128 v[168:171], v176 offset:0
	ds_read_b128 v[172:175], v176 offset:2048
	ds_read_b128 v[176:179], v167 offset:0
	ds_read_b128 v[180:183], v167 offset:2048
	ds_read_b128 v[184:187], v167 offset:4096
	ds_read_b128 v[188:191], v167 offset:6144
	ds_read_b128 v[192:195], v32 offset:0
	ds_read_b128 v[196:199], v32 offset:2048
	ds_read_b128 v[204:207], v239 offset:0
	ds_read_b128 v[244:247], v239 offset:2048
	ds_read_b128 v[248:251], v239 offset:4096
	ds_read_b128 v[200:203], v239 offset:6144
	s_waitcnt lgkmcnt(9)
	v_mfma_f32_32x32x16_bf16 v[114:129], v[176:179], v[168:171], v[114:129]
	v_mfma_f32_32x32x16_bf16 v[98:113], v[176:179], v[172:175], v[98:113]
	s_add_u32 m0, s98, 0x1000
	v_lshl_add_u64 v[176:177], v[148:149], 0, s[16:17]
	global_load_lds_dwordx4 v[176:177], off
	s_waitcnt lgkmcnt(8)
	v_mfma_f32_32x32x16_bf16 v[82:97], v[180:183], v[168:171], v[82:97]
	v_mfma_f32_32x32x16_bf16 v[66:81], v[180:183], v[172:175], v[66:81]
	s_add_u32 m0, s98, 0x2000
	v_lshl_add_u64 v[176:177], v[146:147], 0, s[16:17]
	global_load_lds_dwordx4 v[176:177], off
	s_waitcnt lgkmcnt(7)
	v_mfma_f32_32x32x16_bf16 v[50:65], v[184:187], v[168:171], v[50:65]
	v_mfma_f32_32x32x16_bf16 v[34:49], v[184:187], v[172:175], v[34:49]
	s_add_u32 m0, s98, 0x3000
	v_lshl_add_u64 v[176:177], v[144:145], 0, s[16:17]
	global_load_lds_dwordx4 v[176:177], off
	s_waitcnt lgkmcnt(6)
	v_mfma_f32_32x32x16_bf16 v[16:31], v[188:191], v[168:171], v[16:31]
	v_mfma_f32_32x32x16_bf16 v[0:15], v[188:191], v[172:175], v[0:15]
	s_add_u32 m0, s98, 0x4000
	v_lshl_add_u64 v[176:177], v[142:143], 0, s[16:17]
	global_load_lds_dwordx4 v[176:177], off
	s_waitcnt lgkmcnt(3)
	v_mfma_f32_32x32x16_bf16 v[114:129], v[204:207], v[192:195], v[114:129]
	v_mfma_f32_32x32x16_bf16 v[98:113], v[204:207], v[196:199], v[98:113]
	s_add_u32 m0, s98, 0x5000
	v_lshl_add_u64 v[176:177], v[140:141], 0, s[16:17]
	global_load_lds_dwordx4 v[176:177], off
	s_add_u32 s16, s16, 64
	v_add_u32_e32 v32, 1, v162
	v_cmp_ne_u32_e32 vcc, 2, v162
	s_addc_u32 s17, s17, 0
	s_cmpk_eq_i32 s16, 0x780
	v_cndmask_b32_e32 v162, 0, v32, vcc
	s_waitcnt lgkmcnt(2)
	v_mfma_f32_32x32x16_bf16 v[82:97], v[244:247], v[192:195], v[82:97]
	v_mfma_f32_32x32x16_bf16 v[66:81], v[244:247], v[196:199], v[66:81]
	s_waitcnt lgkmcnt(1)
	v_mfma_f32_32x32x16_bf16 v[50:65], v[248:251], v[192:195], v[50:65]
	v_mfma_f32_32x32x16_bf16 v[34:49], v[248:251], v[196:199], v[34:49]
	s_waitcnt lgkmcnt(0)
	v_mfma_f32_32x32x16_bf16 v[16:31], v[200:203], v[192:195], v[16:31]
	v_mfma_f32_32x32x16_bf16 v[0:15], v[200:203], v[196:199], v[0:15]
	s_cbranch_scc0 .LBB0_210
	v_mul_lo_u32 v32, v162, s84
	v_add_u32_e32 v148, v32, v160
	s_waitcnt vmcnt(6)
	s_barrier
	v_add_u32_e32 v167, v32, v158
	ds_read_b128 v[140:143], v148 offset:0
	ds_read_b128 v[144:147], v148 offset:2048
	ds_read_b128 v[148:151], v167 offset:0
	ds_read_b128 v[168:171], v167 offset:2048
	ds_read_b128 v[172:175], v167 offset:4096
	ds_read_b128 v[176:179], v167 offset:6144
	v_add_u32_e32 v200, v32, v159
	v_add_u32_e32 v32, v32, v161
	ds_read_b128 v[180:183], v32 offset:0
	ds_read_b128 v[184:187], v32 offset:2048
	ds_read_b128 v[188:191], v200 offset:0
	ds_read_b128 v[192:195], v200 offset:2048
	ds_read_b128 v[196:199], v200 offset:4096
	ds_read_b128 v[204:207], v200 offset:6144
	s_waitcnt lgkmcnt(6)
	s_nop 0
	v_mfma_f32_32x32x16_bf16 v[114:129], v[148:151], v[140:143], v[114:129]
	v_mfma_f32_32x32x16_bf16 v[98:113], v[148:151], v[144:147], v[98:113]
	v_mfma_f32_32x32x16_bf16 v[82:97], v[168:171], v[140:143], v[82:97]
	v_mfma_f32_32x32x16_bf16 v[66:81], v[168:171], v[144:147], v[66:81]
	v_mfma_f32_32x32x16_bf16 v[50:65], v[172:175], v[140:143], v[50:65]
	v_mfma_f32_32x32x16_bf16 v[34:49], v[172:175], v[144:147], v[34:49]
	v_mfma_f32_32x32x16_bf16 v[16:31], v[176:179], v[140:143], v[16:31]
	v_mfma_f32_32x32x16_bf16 v[0:15], v[176:179], v[144:147], v[0:15]
	s_waitcnt lgkmcnt(0)
	s_waitcnt vmcnt(0)
	v_add_u32_e32 v32, 1, v162
	v_mfma_f32_32x32x16_bf16 v[114:129], v[188:191], v[180:183], v[114:129]
	v_cmp_ne_u32_e32 vcc, 2, v162
	s_cmp_lg_u64 s[12:13], 0
	s_barrier
; DI void dma_issue(const bf16_t* Ag, size_t lda, const bf16_t* Bg, size_t ldb, int kt, bf16_t* stage, int wid, int lane) {
;   const int rl = lane >> 2, c = (lane & 3) ^ ((lane >> 4) & 3);
; #pragma unroll
;   for (int i = 0; i < 4; ++i) {
;     const int j = wid + 4 * i;
;     __builtin_amdgcn_global_load_lds((const unsigned*)(Ag + (size_t)(16 * j + rl) * lda + kt * 32 + c * 8), (unsigned*)(stage + j * 512), 16, 0, 0);
;   }
; #pragma unroll
;   for (int i = 0; i < 2; ++i) {
;     const int j = wid + 4 * i;
;     __builtin_amdgcn_global_load_lds((const unsigned*)(Bg + (size_t)(16 * j + rl) * ldb + kt * 32 + c * 8), (unsigned*)(stage + STG_A + j * 512), 16, 0, 0);
;   }
; }
; template <bool VT>
; DI int gemm_kloop(const bf16_t* Ag, size_t lda, const bf16_t* Bg, size_t ldb, int nk, bf16_t* ring, f32x16 (&acc)[4][2], int tid, int wm, int wn,
;                   int r, int h, int st0, bool pre, const bf16_t* AgN, const bf16_t* BgN) {
;     ...
;   if (AgN) {
;     const int s1 = st == 2 ? 0 : st + 1, s2 = s1 == 2 ? 0 : s1 + 1;
;     dma_issue(AgN, lda, BgN, ldb, 0, ring + s1 * STG, wid, lane);
;     dma_issue(AgN, lda, BgN, ldb, 1, ring + s2 * STG, wid, lane);
;   }
;   {
;     const unsigned so = (unsigned)st * (unsigned)(STG * 2);
;     g_compute_asm<VT>(oA0 + so, oA1 + so, oB0 + so, oB1 + so, acc);
	v_cndmask_b32_e32 v140, 0, v32, vcc
	v_mfma_f32_32x32x16_bf16 v[98:113], v[188:191], v[184:187], v[98:113]
	v_mfma_f32_32x32x16_bf16 v[82:97], v[192:195], v[180:183], v[82:97]
	v_mfma_f32_32x32x16_bf16 v[66:81], v[192:195], v[184:187], v[66:81]
	v_mfma_f32_32x32x16_bf16 v[50:65], v[196:199], v[180:183], v[50:65]
	v_mfma_f32_32x32x16_bf16 v[34:49], v[196:199], v[184:187], v[34:49]
	v_mfma_f32_32x32x16_bf16 v[16:31], v[204:207], v[180:183], v[16:31]
	v_mfma_f32_32x32x16_bf16 v[0:15], v[204:207], v[184:187], v[0:15]
	s_cbranch_scc0 .LBB0_213
	v_add_u32_e32 v32, 1, v140
	v_cmp_ne_u32_e32 vcc, 2, v140
	v_lshlrev_b32_e32 v149, 1, v164
	v_lshlrev_b32_e32 v151, 1, v163
	v_cndmask_b32_e32 v32, 0, v32, vcc
	v_mul_lo_u32 v141, v32, s95
	v_lshlrev_b32_e32 v148, 1, v141
	v_add_u32_e32 v150, v148, v149
	v_lshl_add_u64 v[142:143], s[12:13], 0, v[138:139]
	v_lshlrev_b64 v[130:131], 1, v[130:131]
	v_readfirstlane_b32 s12, v150
	v_add_u32_e32 v162, v148, v151
	v_lshl_add_u64 v[144:145], v[142:143], 0, v[130:131]
	s_mov_b32 m0, s12
	v_lshlrev_b64 v[132:133], 1, v[132:133]
	v_readfirstlane_b32 s12, v162
	v_add_u32_e32 v163, v148, v166
	global_load_lds_dwordx4 v[144:145], off
	v_lshl_add_u64 v[146:147], v[142:143], 0, v[132:133]
	s_mov_b32 m0, s12
	v_lshl_add_u64 v[134:135], v[134:135], 1, v[142:143]
	v_readfirstlane_b32 s12, v163
	v_lshl_add_u64 v[136:137], v[136:137], 1, v[142:143]
	v_add_u32_e32 v142, v148, v165
	global_load_lds_dwordx4 v[146:147], off
	s_mov_b32 m0, s12
	v_readfirstlane_b32 s12, v142
	v_lshl_add_u64 v[138:139], s[14:15], 0, v[138:139]
	v_add_u32_e32 v142, 0x4000, v150
	global_load_lds_dwordx4 v[134:135], off
	s_mov_b32 m0, s12
	v_lshl_add_u64 v[130:131], v[138:139], 0, v[130:131]
	v_readfirstlane_b32 s12, v142
	v_lshl_add_u64 v[132:133], v[138:139], 0, v[132:133]
	v_add_u32_e32 v138, 0x4000, v162
	global_load_lds_dwordx4 v[136:137], off
	s_mov_b32 m0, s12
	v_readfirstlane_b32 s12, v138
	v_add_u32_e32 v138, 0x3000, v141
	v_cmp_ne_u32_e32 vcc, 2, v32
	global_load_lds_dwordx4 v[130:131], off
	s_nop 0
	v_cndmask_b32_e32 v32, 0, v138, vcc
	v_lshlrev_b32_e32 v32, 1, v32
	v_add_u32_e32 v141, v32, v149
	s_mov_b32 m0, s12
	v_readfirstlane_b32 s12, v141
	v_add_u32_e32 v142, v32, v151
	global_load_lds_dwordx4 v[132:133], off
	v_lshl_add_u64 v[138:139], v[144:145], 0, 64
	s_mov_b32 m0, s12
	v_readfirstlane_b32 s12, v142
	global_load_lds_dwordx4 v[138:139], off
	v_lshl_add_u64 v[138:139], v[146:147], 0, 64
	s_mov_b32 m0, s12
	v_lshl_add_u64 v[134:135], v[134:135], 0, 64
	global_load_lds_dwordx4 v[138:139], off
	v_add_u32_e32 v138, v32, v166
	v_add_u32_e32 v32, v32, v165
	v_readfirstlane_b32 s12, v138
	s_mov_b32 m0, s12
	v_readfirstlane_b32 s12, v32
	v_add_u32_e32 v32, 0x4000, v141
	global_load_lds_dwordx4 v[134:135], off
	v_lshl_add_u64 v[134:135], v[136:137], 0, 64
	s_mov_b32 m0, s12
	v_readfirstlane_b32 s12, v32
	v_add_u32_e32 v32, 0x4000, v142
	global_load_lds_dwordx4 v[134:135], off
	v_lshl_add_u64 v[130:131], v[130:131], 0, 64
	s_mov_b32 m0, s12
	v_readfirstlane_b32 s12, v32
	global_load_lds_dwordx4 v[130:131], off
	v_lshl_add_u64 v[130:131], v[132:133], 0, 64
	s_mov_b32 m0, s12
	s_nop 0
	global_load_lds_dwordx4 v[130:131], off

; template <bool VT>
; DI int gemm_kloop(const bf16_t* Ag, size_t lda, const bf16_t* Bg, size_t ldb, int nk, bf16_t* ring, f32x16 (&acc)[4][2], int tid, int wm, int wn,
;                   int r, int h, int st0, bool pre, const bf16_t* AgN, const bf16_t* BgN) {
;   const int wid = tid >> 6, lane = tid & 63;
;   const unsigned base = (unsigned)(unsigned long long)ring;
;   const int q = (r >> 2) & 3;
;   const unsigned rA = base + (unsigned)(wm * 128 + r) * 64u, rB = base + (unsigned)STG_A * 2u + (unsigned)(wn * 64 + r) * 64u;
;   const unsigned oA0 = rA + (unsigned)((h ^ q) & 3) * 16u, oA1 = rA + (unsigned)(((2 + h) ^ q) & 3) * 16u;
;   const unsigned oB0 = rB + (unsigned)((h ^ q) & 3) * 16u, oB1 = rB + (unsigned)(((2 + h) ^ q) & 3) * 16u;
;   int st = st0;
;     ...
;   const bf16_t* Ag = A + (size_t)m0 * lda;
;   const bf16_t* Bg = Bt + (size_t)n0 * ldb;
;   if (ssq) {
;     const f32x4* sp = (const f32x4*)(ssq + (size_t)(m0 + tid) * 16);
;     const f32x4 a = sp[0], b = sp[1], c = sp[2], d = sp[3];
;     const float tot = ((a.x + a.y) + (a.z + a.w)) + ((b.x + b.y) + (b.z + b.w)) + ((c.x + c.y) + (c.z + c.w)) + ((d.x + d.y) + (d.z + d.w));
;     sR[tid] = rsqrtf(tot * (1.f / DM) + 1e-6f);
;   }
;   __syncthreads();
;   f32x16 acc[4][2];
; #pragma unroll
;   for (int a = 0; a < 4; ++a)
; #pragma unroll
;     for (int b = 0; b < 2; ++b)
; #pragma unroll
;       for (int i = 0; i < 16; ++i) acc[a][b][i] = 0.f;
;   const bool vt = epi.vtype(n0 + wn * 64);
;   int st_last = 0;
.LBB0_644:
	v_lshlrev_b64 v[138:139], 1, v[32:33]
	s_add_u32 s46, s63, s52
	v_lshlrev_b32_e32 v165, 10, v0
	v_lshlrev_b32_e32 v164, 10, v1
	v_lshl_add_u64 v[0:1], v[132:133], 1, v[138:139]
	s_addc_u32 s47, s64, s53
	v_lshl_add_u64 v[2:3], v[130:131], 1, v[138:139]
	v_lshl_add_u64 v[140:141], s[46:47], 0, v[0:1]
	v_lshl_add_u64 v[142:143], s[46:47], 0, v[2:3]
	s_add_i32 s46, s50, s54
	s_lshl_b32 s46, s46, 11
	s_or_b32 s55, s46, s51
	v_lshlrev_b64 v[4:5], 1, v[136:137]
	v_mad_i64_i32 v[4:5], s[46:47], s55, v211, v[4:5]
	v_lshl_add_u64 v[4:5], v[4:5], 0, v[138:139]
	v_lshl_add_u64 v[144:145], s[28:29], 0, v[4:5]
	v_lshlrev_b64 v[4:5], 1, v[134:135]
	v_mad_i64_i32 v[4:5], s[46:47], s55, v211, v[4:5]
	v_mad_i64_i32 v[0:1], s[46:47], s55, v211, v[0:1]
	v_lshl_add_u64 v[4:5], v[4:5], 0, v[138:139]
	v_lshl_add_u64 v[148:149], s[28:29], 0, v[0:1]
	v_mad_i64_i32 v[0:1], s[46:47], s55, v211, v[2:3]
	v_mov_b32_e32 v16, 0
	v_lshl_add_u64 v[146:147], s[28:29], 0, v[4:5]
	v_lshl_add_u64 v[150:151], s[28:29], 0, v[0:1]
	s_mov_b64 s[46:47], 0
	s_mov_b32 s55, s48
	v_mov_b32_e32 v17, v16
	v_mov_b32_e32 v18, v16
	v_mov_b32_e32 v19, v16
	v_mov_b32_e32 v20, v16
	v_mov_b32_e32 v21, v16
	v_mov_b32_e32 v22, v16
	v_mov_b32_e32 v23, v16
	v_mov_b32_e32 v24, v16
	v_mov_b32_e32 v25, v16
	v_mov_b32_e32 v26, v16
	v_mov_b32_e32 v27, v16
	v_mov_b32_e32 v28, v16
	v_mov_b32_e32 v29, v16
	v_mov_b32_e32 v30, v16
	v_mov_b32_e32 v31, v16
	v_mov_b32_e32 v0, v16
	v_mov_b32_e32 v1, v16
	v_mov_b32_e32 v2, v16
	v_mov_b32_e32 v3, v16
	v_mov_b32_e32 v4, v16
	v_mov_b32_e32 v5, v16
	v_mov_b32_e32 v6, v16
	v_mov_b32_e32 v7, v16
	v_mov_b32_e32 v8, v16
	v_mov_b32_e32 v9, v16
	v_mov_b32_e32 v10, v16
	v_mov_b32_e32 v11, v16
	v_mov_b32_e32 v12, v16
	v_mov_b32_e32 v13, v16
	v_mov_b32_e32 v14, v16
	v_mov_b32_e32 v15, v16
	v_mov_b32_e32 v50, v16
	v_mov_b32_e32 v51, v16
	v_mov_b32_e32 v52, v16
	v_mov_b32_e32 v53, v16
	v_mov_b32_e32 v54, v16
	v_mov_b32_e32 v55, v16
	v_mov_b32_e32 v56, v16
	v_mov_b32_e32 v57, v16
	v_mov_b32_e32 v58, v16
	v_mov_b32_e32 v59, v16
	v_mov_b32_e32 v60, v16
	v_mov_b32_e32 v61, v16
	v_mov_b32_e32 v62, v16
	v_mov_b32_e32 v63, v16
	v_mov_b32_e32 v64, v16
	v_mov_b32_e32 v65, v16
	v_mov_b32_e32 v34, v16
	v_mov_b32_e32 v35, v16
	v_mov_b32_e32 v36, v16
	v_mov_b32_e32 v37, v16
	v_mov_b32_e32 v38, v16
	v_mov_b32_e32 v39, v16
	v_mov_b32_e32 v40, v16
	v_mov_b32_e32 v41, v16
	v_mov_b32_e32 v42, v16
	v_mov_b32_e32 v43, v16
	v_mov_b32_e32 v44, v16
	v_mov_b32_e32 v45, v16
	v_mov_b32_e32 v46, v16
	v_mov_b32_e32 v47, v16
	v_mov_b32_e32 v48, v16
	v_mov_b32_e32 v49, v16
	v_mov_b32_e32 v82, v16
	v_mov_b32_e32 v83, v16
	v_mov_b32_e32 v84, v16
	v_mov_b32_e32 v85, v16
	v_mov_b32_e32 v86, v16
	v_mov_b32_e32 v87, v16
	v_mov_b32_e32 v88, v16
	v_mov_b32_e32 v89, v16
	v_mov_b32_e32 v90, v16
	v_mov_b32_e32 v91, v16
	v_mov_b32_e32 v92, v16
	v_mov_b32_e32 v93, v16
	v_mov_b32_e32 v94, v16
	v_mov_b32_e32 v95, v16
	v_mov_b32_e32 v96, v16
	v_mov_b32_e32 v97, v16
	v_mov_b32_e32 v66, v16
	v_mov_b32_e32 v67, v16
	v_mov_b32_e32 v68, v16
	v_mov_b32_e32 v69, v16
	v_mov_b32_e32 v70, v16
	v_mov_b32_e32 v71, v16
	v_mov_b32_e32 v72, v16
	v_mov_b32_e32 v73, v16
	v_mov_b32_e32 v74, v16
	v_mov_b32_e32 v75, v16
	v_mov_b32_e32 v76, v16
	v_mov_b32_e32 v77, v16
	v_mov_b32_e32 v78, v16
	v_mov_b32_e32 v79, v16
	v_mov_b32_e32 v80, v16
	v_mov_b32_e32 v81, v16
	v_mov_b32_e32 v114, v16
	v_mov_b32_e32 v115, v16
	v_mov_b32_e32 v116, v16
	v_mov_b32_e32 v117, v16
	v_mov_b32_e32 v118, v16
	v_mov_b32_e32 v119, v16
	v_mov_b32_e32 v120, v16
	v_mov_b32_e32 v121, v16
	v_mov_b32_e32 v122, v16
	v_mov_b32_e32 v123, v16
	v_mov_b32_e32 v124, v16
	v_mov_b32_e32 v125, v16
	v_mov_b32_e32 v126, v16
	v_mov_b32_e32 v127, v16
	v_mov_b32_e32 v128, v16
	v_mov_b32_e32 v129, v16
	v_mov_b32_e32 v98, v16
	v_mov_b32_e32 v99, v16
	v_mov_b32_e32 v100, v16
	v_mov_b32_e32 v101, v16
	v_mov_b32_e32 v102, v16
	v_mov_b32_e32 v103, v16
	v_mov_b32_e32 v104, v16
	v_mov_b32_e32 v105, v16
	v_mov_b32_e32 v106, v16
	v_mov_b32_e32 v107, v16
	v_mov_b32_e32 v108, v16
	v_mov_b32_e32 v109, v16
	v_mov_b32_e32 v110, v16
	v_mov_b32_e32 v111, v16
	v_mov_b32_e32 v112, v16
	v_mov_b32_e32 v113, v16
	v_readfirstlane_b32 s99, v162
	s_lshl_b32 s99, s99, 1
.LBB0_645:
	s_mul_i32 s56, s55, 0x3000
	v_lshl_add_u64 v[166:167], v[150:151], 0, s[46:47]
	s_mul_i32 s98, s55, 0x3000
	s_addk_i32 s98, 0xd000
	s_cmp_lg_u32 s55, 0
	s_cselect_b32 s98, s98, 0x6000
	s_lshl_b32 s98, s98, 1
	s_add_u32 s98, s98, s99
	s_mul_i32 s56, s55, 0x6000
	v_add_u32_e32 v174, s56, v159
	v_add_u32_e32 v32, s56, v157
	v_add_u32_e32 v198, s56, v160
	v_add_u32_e32 v202, s56, v158
	s_mov_b32 m0, s98
	s_waitcnt vmcnt(6)
	s_barrier
; template <bool VT>
; DI void g_compute_asm(unsigned aA0, unsigned aA1, unsigned aB0, unsigned aB1, f32x16 (&acc)[4][2]) {
;   bf16x8 a0[4], a1[4], b0[2], b1[2];
;   DSR(b0[0], aB0, 0); DSR(b0[1], aB0, 2048);
;   DSR(a0[0], aA0, 0); DSR(a0[1], aA0, 2048); DSR(a0[2], aA0, 4096); DSR(a0[3], aA0, 6144);
;   DSR(b1[0], aB1, 0); DSR(b1[1], aB1, 2048);
;   DSR(a1[0], aA1, 0); DSR(a1[1], aA1, 2048); DSR(a1[2], aA1, 4096); DSR(a1[3], aA1, 6144);
;   asm volatile("s_waitcnt lgkmcnt(6)" : "+v"(b0[0]), "+v"(b0[1]), "+v"(a0[0]), "+v"(a0[1]), "+v"(a0[2]), "+v"(a0[3]));
; #pragma unroll
;   for (int mi = 0; mi < 4; ++mi)
; #pragma unroll
;     for (int ni = 0; ni < 2; ++ni) {
;       if (VT) acc[mi][ni] = MFMA(a0[mi], b0[ni], acc[mi][ni]);
;       else acc[mi][ni] = MFMA(b0[ni], a0[mi], acc[mi][ni]);
;     }
;   __builtin_amdgcn_sched_barrier(0);
;   asm volatile("s_waitcnt lgkmcnt(0)" : "+v"(b1[0]), "+v"(b1[1]), "+v"(a1[0]), "+v"(a1[1]), "+v"(a1[2]), "+v"(a1[3]));
; #pragma unroll
;   for (int mi = 0; mi < 4; ++mi)
; #pragma unroll
;     for (int ni = 0; ni < 2; ++ni) {
;       if (VT) acc[mi][ni] = MFMA(a1[mi], b1[ni], acc[mi][ni]);
;       else acc[mi][ni] = MFMA(b1[ni], a1[mi], acc[mi][ni]);
;     }
; }
; template <bool VT>
; DI int gemm_kloop(const bf16_t* Ag, size_t lda, const bf16_t* Bg, size_t ldb, int nk, bf16_t* ring, f32x16 (&acc)[4][2], int tid, int wm, int wn,
;                   int r, int h, int st0, bool pre, const bf16_t* AgN, const bf16_t* BgN) {
;     ...
;   for (int kt = 0; kt < nk - 1; ++kt) {
;     asm volatile("s_waitcnt vmcnt(6)" ::: "memory");
;     __builtin_amdgcn_s_barrier();
;     if (kt + 2 < nk) dma_issue(Ag, lda, Bg, ldb, kt + 2, ring + (st == 0 ? 2 : st - 1) * STG, wid, lane);
;     const unsigned so = (unsigned)st * (unsigned)(STG * 2);
;     g_compute_asm<VT>(oA0 + so, oA1 + so, oB0 + so, oB1 + so, acc);
;     st = st == 2 ? 0 : st + 1;
;   }
;   asm volatile("s_waitcnt vmcnt(0)" ::: "memory");
;   __builtin_amdgcn_s_barrier();
;   if (AgN) {
;     const int s1 = st == 2 ? 0 : st + 1, s2 = s1 == 2 ? 0 : s1 + 1;
;     dma_issue(AgN, lda, BgN, ldb, 0, ring + s1 * STG, wid, lane);
;     dma_issue(AgN, lda, BgN, ldb, 1, ring + s2 * STG, wid, lane);
;   }
;   {
;     const unsigned so = (unsigned)st * (unsigned)(STG * 2);
;     g_compute_asm<VT>(oA0 + so, oA1 + so, oB0 + so, oB1 + so, acc);
	global_load_lds_dwordx4 v[166:167], off
	ds_read_b128 v[166:169], v174 offset:0
	ds_read_b128 v[170:173], v174 offset:2048
	ds_read_b128 v[174:177], v32 offset:0
	ds_read_b128 v[178:181], v32 offset:2048
	ds_read_b128 v[182:185], v32 offset:4096
	ds_read_b128 v[186:189], v32 offset:6144
	ds_read_b128 v[190:193], v198 offset:0
	ds_read_b128 v[194:197], v198 offset:2048
	ds_read_b128 v[198:201], v202 offset:0
	ds_read_b128 v[204:207], v202 offset:2048
	ds_read_b128 v[244:247], v202 offset:4096
	ds_read_b128 v[248:251], v202 offset:6144
	s_waitcnt lgkmcnt(9)
	v_mfma_f32_32x32x16_bf16 v[98:113], v[166:169], v[174:177], v[98:113]
	v_mfma_f32_32x32x16_bf16 v[114:129], v[170:173], v[174:177], v[114:129]
	s_add_u32 m0, s98, 0x1000
	v_lshl_add_u64 v[174:175], v[148:149], 0, s[46:47]
	global_load_lds_dwordx4 v[174:175], off
	s_waitcnt lgkmcnt(8)
	v_mfma_f32_32x32x16_bf16 v[66:81], v[166:169], v[178:181], v[66:81]
	v_mfma_f32_32x32x16_bf16 v[82:97], v[170:173], v[178:181], v[82:97]
	s_add_u32 m0, s98, 0x2000
	v_lshl_add_u64 v[174:175], v[146:147], 0, s[46:47]
	global_load_lds_dwordx4 v[174:175], off
	s_waitcnt lgkmcnt(7)
	v_mfma_f32_32x32x16_bf16 v[34:49], v[166:169], v[182:185], v[34:49]
	v_mfma_f32_32x32x16_bf16 v[50:65], v[170:173], v[182:185], v[50:65]
	s_add_u32 m0, s98, 0x3000
	v_lshl_add_u64 v[174:175], v[144:145], 0, s[46:47]
	global_load_lds_dwordx4 v[174:175], off
	s_waitcnt lgkmcnt(6)
	v_mfma_f32_32x32x16_bf16 v[0:15], v[166:169], v[186:189], v[0:15]
	v_mfma_f32_32x32x16_bf16 v[16:31], v[170:173], v[186:189], v[16:31]
	s_add_u32 m0, s98, 0x4000
	v_lshl_add_u64 v[174:175], v[142:143], 0, s[46:47]
	global_load_lds_dwordx4 v[174:175], off
	s_waitcnt lgkmcnt(3)
	v_mfma_f32_32x32x16_bf16 v[98:113], v[190:193], v[198:201], v[98:113]
	v_mfma_f32_32x32x16_bf16 v[114:129], v[194:197], v[198:201], v[114:129]
	s_add_u32 m0, s98, 0x5000
	v_lshl_add_u64 v[174:175], v[140:141], 0, s[46:47]
	global_load_lds_dwordx4 v[174:175], off
	s_add_i32 s56, s55, 1
	s_cmp_lg_u32 s55, 2
	s_cselect_b32 s55, s56, 0
	s_add_u32 s46, s46, 64
	s_addc_u32 s47, s47, 0
	s_cmpk_eq_i32 s46, 0x780
	s_waitcnt lgkmcnt(2)
	v_mfma_f32_32x32x16_bf16 v[66:81], v[190:193], v[204:207], v[66:81]
	v_mfma_f32_32x32x16_bf16 v[82:97], v[194:197], v[204:207], v[82:97]
	s_waitcnt lgkmcnt(1)
	v_mfma_f32_32x32x16_bf16 v[34:49], v[190:193], v[244:247], v[34:49]
	v_mfma_f32_32x32x16_bf16 v[50:65], v[194:197], v[244:247], v[50:65]
	s_waitcnt lgkmcnt(0)
	v_mfma_f32_32x32x16_bf16 v[0:15], v[190:193], v[248:251], v[0:15]
	v_mfma_f32_32x32x16_bf16 v[16:31], v[194:197], v[248:251], v[16:31]
	s_cbranch_scc0 .LBB0_645
	s_mul_i32 s46, s55, 0x6000
	v_add_u32_e32 v148, s46, v159
	s_waitcnt vmcnt(6)
	s_barrier
	v_add_u32_e32 v32, s46, v157
	v_add_u32_e32 v186, s46, v160
	ds_read_b128 v[140:143], v148 offset:0
	ds_read_b128 v[144:147], v148 offset:2048
	ds_read_b128 v[148:151], v32 offset:0
	ds_read_b128 v[166:169], v32 offset:2048
	ds_read_b128 v[170:173], v32 offset:4096
	ds_read_b128 v[174:177], v32 offset:6144
	v_add_u32_e32 v202, s46, v158
	ds_read_b128 v[178:181], v186 offset:0
	ds_read_b128 v[182:185], v186 offset:2048
	ds_read_b128 v[186:189], v202 offset:0
	ds_read_b128 v[190:193], v202 offset:2048
	ds_read_b128 v[194:197], v202 offset:4096
	ds_read_b128 v[198:201], v202 offset:6144
	s_waitcnt lgkmcnt(6)
	s_nop 0
	v_mfma_f32_32x32x16_bf16 v[98:113], v[140:143], v[148:151], v[98:113]
	v_mfma_f32_32x32x16_bf16 v[114:129], v[144:147], v[148:151], v[114:129]
	v_mfma_f32_32x32x16_bf16 v[66:81], v[140:143], v[166:169], v[66:81]
	v_mfma_f32_32x32x16_bf16 v[82:97], v[144:147], v[166:169], v[82:97]
	v_mfma_f32_32x32x16_bf16 v[34:49], v[140:143], v[170:173], v[34:49]
	v_mfma_f32_32x32x16_bf16 v[50:65], v[144:147], v[170:173], v[50:65]
	v_mfma_f32_32x32x16_bf16 v[0:15], v[140:143], v[174:177], v[0:15]
	v_mfma_f32_32x32x16_bf16 v[16:31], v[144:147], v[174:177], v[16:31]
	s_waitcnt lgkmcnt(0)
	s_add_i32 s46, s55, 1
	v_mfma_f32_32x32x16_bf16 v[98:113], v[178:181], v[186:189], v[98:113]
	s_waitcnt vmcnt(0)
	s_cmp_lg_u32 s55, 2
	s_cselect_b32 s67, s46, 0
	s_cmp_lg_u64 s[36:37], 0
	s_barrier
; DI void dma_issue(const bf16_t* Ag, size_t lda, const bf16_t* Bg, size_t ldb, int kt, bf16_t* stage, int wid, int lane) {
;   const int rl = lane >> 2, c = (lane & 3) ^ ((lane >> 4) & 3);
; #pragma unroll
;   for (int i = 0; i < 4; ++i) {
;     const int j = wid + 4 * i;
;     __builtin_amdgcn_global_load_lds((const unsigned*)(Ag + (size_t)(16 * j + rl) * lda + kt * 32 + c * 8), (unsigned*)(stage + j * 512), 16, 0, 0);
;   }
; #pragma unroll
;   for (int i = 0; i < 2; ++i) {
;     const int j = wid + 4 * i;
;     __builtin_amdgcn_global_load_lds((const unsigned*)(Bg + (size_t)(16 * j + rl) * ldb + kt * 32 + c * 8), (unsigned*)(stage + STG_A + j * 512), 16, 0, 0);
;   }
; }
; template <bool VT>
; DI int gemm_kloop(const bf16_t* Ag, size_t lda, const bf16_t* Bg, size_t ldb, int nk, bf16_t* ring, f32x16 (&acc)[4][2], int tid, int wm, int wn,
;                   int r, int h, int st0, bool pre, const bf16_t* AgN, const bf16_t* BgN) {
;     ...
;   if (AgN) {
;     const int s1 = st == 2 ? 0 : st + 1, s2 = s1 == 2 ? 0 : s1 + 1;
;     dma_issue(AgN, lda, BgN, ldb, 0, ring + s1 * STG, wid, lane);
;     dma_issue(AgN, lda, BgN, ldb, 1, ring + s2 * STG, wid, lane);
;   }
;   {
;     const unsigned so = (unsigned)st * (unsigned)(STG * 2);
;     g_compute_asm<VT>(oA0 + so, oA1 + so, oB0 + so, oB1 + so, acc);
	v_mfma_f32_32x32x16_bf16 v[114:129], v[182:185], v[186:189], v[114:129]
	v_mfma_f32_32x32x16_bf16 v[66:81], v[178:181], v[190:193], v[66:81]
	v_mfma_f32_32x32x16_bf16 v[82:97], v[182:185], v[190:193], v[82:97]
	v_mfma_f32_32x32x16_bf16 v[34:49], v[178:181], v[194:197], v[34:49]
	v_mfma_f32_32x32x16_bf16 v[50:65], v[182:185], v[194:197], v[50:65]
	v_mfma_f32_32x32x16_bf16 v[0:15], v[178:181], v[198:201], v[0:15]
	v_mfma_f32_32x32x16_bf16 v[16:31], v[182:185], v[198:201], v[16:31]
	s_cbranch_scc0 .LBB0_648
	s_add_i32 s46, s67, 1
	s_cmp_lg_u32 s67, 2
	s_cselect_b32 s46, s46, 0
	s_mul_i32 s47, s46, 0x3000
	s_lshl_b32 s55, s47, 1
	v_lshlrev_b32_e32 v32, 1, v162
	v_add_u32_e32 v146, s55, v32
	v_lshlrev_b32_e32 v147, 1, v163
	v_lshl_add_u64 v[140:141], s[36:37], 0, v[138:139]
	v_lshlrev_b64 v[130:131], 1, v[130:131]
	v_readfirstlane_b32 s56, v146
	v_add_u32_e32 v148, s55, v147
	v_lshl_add_u64 v[142:143], v[140:141], 0, v[130:131]
	s_mov_b32 m0, s56
	v_lshlrev_b64 v[132:133], 1, v[132:133]
	v_readfirstlane_b32 s56, v148
	v_add_u32_e32 v149, s55, v165
	s_addk_i32 s47, 0x3000
	global_load_lds_dwordx4 v[142:143], off
	v_lshl_add_u64 v[144:145], v[140:141], 0, v[132:133]
	s_mov_b32 m0, s56
	v_lshl_add_u64 v[134:135], v[134:135], 1, v[140:141]
	v_readfirstlane_b32 s56, v149
	v_lshl_add_u64 v[136:137], v[136:137], 1, v[140:141]
	v_add_u32_e32 v140, s55, v164
	s_cmp_lg_u32 s46, 2
	global_load_lds_dwordx4 v[144:145], off
	s_mov_b32 m0, s56
	v_readfirstlane_b32 s55, v140
	v_lshl_add_u64 v[138:139], s[38:39], 0, v[138:139]
	v_add_u32_e32 v140, 0x4000, v146
	s_cselect_b32 s46, s47, 0
	global_load_lds_dwordx4 v[134:135], off
	s_mov_b32 m0, s55
	v_lshl_add_u64 v[130:131], v[138:139], 0, v[130:131]
	v_readfirstlane_b32 s55, v140
	v_lshl_add_u64 v[132:133], v[138:139], 0, v[132:133]
	v_add_u32_e32 v138, 0x4000, v148
	s_lshl_b32 s46, s46, 1
	global_load_lds_dwordx4 v[136:137], off
	s_mov_b32 m0, s55
	v_readfirstlane_b32 s55, v138
	v_add_u32_e32 v32, s46, v32
	global_load_lds_dwordx4 v[130:131], off
	s_mov_b32 m0, s55
	v_readfirstlane_b32 s47, v32
	v_add_u32_e32 v140, s46, v147
	global_load_lds_dwordx4 v[132:133], off
	v_lshl_add_u64 v[138:139], v[142:143], 0, 64
	s_mov_b32 m0, s47
	v_readfirstlane_b32 s47, v140
	global_load_lds_dwordx4 v[138:139], off
	v_lshl_add_u64 v[138:139], v[144:145], 0, 64
	s_mov_b32 m0, s47
	v_lshl_add_u64 v[134:135], v[134:135], 0, 64
	global_load_lds_dwordx4 v[138:139], off
	v_add_u32_e32 v138, s46, v165
	v_add_u32_e32 v32, 0x4000, v32
	v_readfirstlane_b32 s47, v138
	s_mov_b32 m0, s47
	v_lshl_add_u64 v[130:131], v[130:131], 0, 64
	global_load_lds_dwordx4 v[134:135], off
	v_lshl_add_u64 v[134:135], v[136:137], 0, 64
	v_add_u32_e32 v136, s46, v164
	s_nop 0
	v_readfirstlane_b32 s46, v136
	s_mov_b32 m0, s46
	v_readfirstlane_b32 s46, v32
	v_add_u32_e32 v32, 0x4000, v140
	global_load_lds_dwordx4 v[134:135], off
	s_mov_b32 m0, s46
	v_readfirstlane_b32 s46, v32
	global_load_lds_dwordx4 v[130:131], off
	v_lshl_add_u64 v[130:131], v[132:133], 0, 64
	s_mov_b32 m0, s46
	s_nop 0
	global_load_lds_dwordx4 v[130:131], off

; template <bool VT>
; DI int gemm_kloop(const bf16_t* Ag, size_t lda, const bf16_t* Bg, size_t ldb, int nk, bf16_t* ring, f32x16 (&acc)[4][2], int tid, int wm, int wn,
;                   int r, int h, int st0, bool pre, const bf16_t* AgN, const bf16_t* BgN) {
;   const int wid = tid >> 6, lane = tid & 63;
;   const unsigned base = (unsigned)(unsigned long long)ring;
;   const int q = (r >> 2) & 3;
;   const unsigned rA = base + (unsigned)(wm * 128 + r) * 64u, rB = base + (unsigned)STG_A * 2u + (unsigned)(wn * 64 + r) * 64u;
;   const unsigned oA0 = rA + (unsigned)((h ^ q) & 3) * 16u, oA1 = rA + (unsigned)(((2 + h) ^ q) & 3) * 16u;
;   const unsigned oB0 = rB + (unsigned)((h ^ q) & 3) * 16u, oB1 = rB + (unsigned)(((2 + h) ^ q) & 3) * 16u;
;   int st = st0;
;     ...
;   const bf16_t* Ag = A + (size_t)m0 * lda;
;   const bf16_t* Bg = Bt + (size_t)n0 * ldb;
;   if (ssq) {
;     const f32x4* sp = (const f32x4*)(ssq + (size_t)(m0 + tid) * 16);
;     const f32x4 a = sp[0], b = sp[1], c = sp[2], d = sp[3];
;     const float tot = ((a.x + a.y) + (a.z + a.w)) + ((b.x + b.y) + (b.z + b.w)) + ((c.x + c.y) + (c.z + c.w)) + ((d.x + d.y) + (d.z + d.w));
;     sR[tid] = rsqrtf(tot * (1.f / DM) + 1e-6f);
;   }
;   __syncthreads();
;   f32x16 acc[4][2];
; #pragma unroll
;   for (int a = 0; a < 4; ++a)
; #pragma unroll
;     for (int b = 0; b < 2; ++b)
; #pragma unroll
;       for (int i = 0; i < 16; ++i) acc[a][b][i] = 0.f;
;   const bool vt = epi.vtype(n0 + wn * 64);
;   int st_last = 0;
.LBB0_654:
	v_lshlrev_b64 v[138:139], 1, v[32:33]
	s_add_u32 s40, s63, s52
	v_lshl_add_u64 v[0:1], v[132:133], 1, v[138:139]
	s_addc_u32 s41, s64, s53
	v_lshl_add_u64 v[2:3], v[130:131], 1, v[138:139]
	s_add_i32 s50, s50, s54
	v_lshl_add_u64 v[140:141], s[40:41], 0, v[0:1]
	v_lshl_add_u64 v[142:143], s[40:41], 0, v[2:3]
	s_lshl_b32 s40, s50, 11
	s_or_b32 s42, s40, s51
	v_lshlrev_b64 v[4:5], 1, v[136:137]
	v_mad_i64_i32 v[4:5], s[40:41], s42, v211, v[4:5]
	v_lshl_add_u64 v[4:5], v[4:5], 0, v[138:139]
	v_lshl_add_u64 v[144:145], s[28:29], 0, v[4:5]
	v_lshlrev_b64 v[4:5], 1, v[134:135]
	v_mad_i64_i32 v[4:5], s[40:41], s42, v211, v[4:5]
	v_mad_i64_i32 v[0:1], s[40:41], s42, v211, v[0:1]
	v_lshl_add_u64 v[4:5], v[4:5], 0, v[138:139]
	v_lshl_add_u64 v[148:149], s[28:29], 0, v[0:1]
	v_mad_i64_i32 v[0:1], s[40:41], s42, v211, v[2:3]
	v_mov_b32_e32 v16, 0
	v_lshlrev_b32_e32 v164, 10, v8
	v_lshlrev_b32_e32 v163, 10, v10
	v_lshl_add_u64 v[146:147], s[28:29], 0, v[4:5]
	v_lshl_add_u64 v[150:151], s[28:29], 0, v[0:1]
	s_mov_b64 s[40:41], 0
	v_mov_b32_e32 v17, v16
	v_mov_b32_e32 v18, v16
	v_mov_b32_e32 v19, v16
	v_mov_b32_e32 v20, v16
	v_mov_b32_e32 v21, v16
	v_mov_b32_e32 v22, v16
	v_mov_b32_e32 v23, v16
	v_mov_b32_e32 v24, v16
	v_mov_b32_e32 v25, v16
	v_mov_b32_e32 v26, v16
	v_mov_b32_e32 v27, v16
	v_mov_b32_e32 v28, v16
	v_mov_b32_e32 v29, v16
	v_mov_b32_e32 v30, v16
	v_mov_b32_e32 v31, v16
	v_mov_b32_e32 v0, v16
	v_mov_b32_e32 v1, v16
	v_mov_b32_e32 v2, v16
	v_mov_b32_e32 v3, v16
	v_mov_b32_e32 v4, v16
	v_mov_b32_e32 v5, v16
	v_mov_b32_e32 v6, v16
	v_mov_b32_e32 v7, v16
	v_mov_b32_e32 v8, v16
	v_mov_b32_e32 v9, v16
	v_mov_b32_e32 v10, v16
	v_mov_b32_e32 v11, v16
	v_mov_b32_e32 v12, v16
	v_mov_b32_e32 v13, v16
	v_mov_b32_e32 v14, v16
	v_mov_b32_e32 v15, v16
	v_mov_b32_e32 v50, v16
	v_mov_b32_e32 v51, v16
	v_mov_b32_e32 v52, v16
	v_mov_b32_e32 v53, v16
	v_mov_b32_e32 v54, v16
	v_mov_b32_e32 v55, v16
	v_mov_b32_e32 v56, v16
	v_mov_b32_e32 v57, v16
	v_mov_b32_e32 v58, v16
	v_mov_b32_e32 v59, v16
	v_mov_b32_e32 v60, v16
	v_mov_b32_e32 v61, v16
	v_mov_b32_e32 v62, v16
	v_mov_b32_e32 v63, v16
	v_mov_b32_e32 v64, v16
	v_mov_b32_e32 v65, v16
	v_mov_b32_e32 v34, v16
	v_mov_b32_e32 v35, v16
	v_mov_b32_e32 v36, v16
	v_mov_b32_e32 v37, v16
	v_mov_b32_e32 v38, v16
	v_mov_b32_e32 v39, v16
	v_mov_b32_e32 v40, v16
	v_mov_b32_e32 v41, v16
	v_mov_b32_e32 v42, v16
	v_mov_b32_e32 v43, v16
	v_mov_b32_e32 v44, v16
	v_mov_b32_e32 v45, v16
	v_mov_b32_e32 v46, v16
	v_mov_b32_e32 v47, v16
	v_mov_b32_e32 v48, v16
	v_mov_b32_e32 v49, v16
	v_mov_b32_e32 v82, v16
	v_mov_b32_e32 v83, v16
	v_mov_b32_e32 v84, v16
	v_mov_b32_e32 v85, v16
	v_mov_b32_e32 v86, v16
	v_mov_b32_e32 v87, v16
	v_mov_b32_e32 v88, v16
	v_mov_b32_e32 v89, v16
	v_mov_b32_e32 v90, v16
	v_mov_b32_e32 v91, v16
	v_mov_b32_e32 v92, v16
	v_mov_b32_e32 v93, v16
	v_mov_b32_e32 v94, v16
	v_mov_b32_e32 v95, v16
	v_mov_b32_e32 v96, v16
	v_mov_b32_e32 v97, v16
	v_mov_b32_e32 v66, v16
	v_mov_b32_e32 v67, v16
	v_mov_b32_e32 v68, v16
	v_mov_b32_e32 v69, v16
	v_mov_b32_e32 v70, v16
	v_mov_b32_e32 v71, v16
	v_mov_b32_e32 v72, v16
	v_mov_b32_e32 v73, v16
	v_mov_b32_e32 v74, v16
	v_mov_b32_e32 v75, v16
	v_mov_b32_e32 v76, v16
	v_mov_b32_e32 v77, v16
	v_mov_b32_e32 v78, v16
	v_mov_b32_e32 v79, v16
	v_mov_b32_e32 v80, v16
	v_mov_b32_e32 v81, v16
	v_mov_b32_e32 v114, v16
	v_mov_b32_e32 v115, v16
	v_mov_b32_e32 v116, v16
	v_mov_b32_e32 v117, v16
	v_mov_b32_e32 v118, v16
	v_mov_b32_e32 v119, v16
	v_mov_b32_e32 v120, v16
	v_mov_b32_e32 v121, v16
	v_mov_b32_e32 v122, v16
	v_mov_b32_e32 v123, v16
	v_mov_b32_e32 v124, v16
	v_mov_b32_e32 v125, v16
	v_mov_b32_e32 v126, v16
	v_mov_b32_e32 v127, v16
	v_mov_b32_e32 v128, v16
	v_mov_b32_e32 v129, v16
	v_mov_b32_e32 v98, v16
	v_mov_b32_e32 v99, v16
	v_mov_b32_e32 v100, v16
	v_mov_b32_e32 v101, v16
	v_mov_b32_e32 v102, v16
	v_mov_b32_e32 v103, v16
	v_mov_b32_e32 v104, v16
	v_mov_b32_e32 v105, v16
	v_mov_b32_e32 v106, v16
	v_mov_b32_e32 v107, v16
	v_mov_b32_e32 v108, v16
	v_mov_b32_e32 v109, v16
	v_mov_b32_e32 v110, v16
	v_mov_b32_e32 v111, v16
	v_mov_b32_e32 v112, v16
	v_mov_b32_e32 v113, v16
	v_readfirstlane_b32 s99, v162
	s_lshl_b32 s99, s99, 1
.LBB0_655:
	s_mul_i32 s42, s48, 0x3000
	v_lshl_add_u64 v[166:167], v[150:151], 0, s[40:41]
	s_mul_i32 s98, s48, 0x3000
	s_addk_i32 s98, 0xd000
	s_cmp_lg_u32 s48, 0
	s_cselect_b32 s98, s98, 0x6000
	s_lshl_b32 s98, s98, 1
	s_add_u32 s98, s98, s99
	s_mul_i32 s42, s48, 0x6000
	v_add_u32_e32 v174, s42, v159
	v_add_u32_e32 v32, s42, v157
	v_add_u32_e32 v198, s42, v160
	v_add_u32_e32 v165, s42, v158
	s_mov_b32 m0, s98
	s_waitcnt vmcnt(6)
	s_barrier
; template <bool VT>
; DI void g_compute_asm(unsigned aA0, unsigned aA1, unsigned aB0, unsigned aB1, f32x16 (&acc)[4][2]) {
;   bf16x8 a0[4], a1[4], b0[2], b1[2];
;   DSR(b0[0], aB0, 0); DSR(b0[1], aB0, 2048);
;   DSR(a0[0], aA0, 0); DSR(a0[1], aA0, 2048); DSR(a0[2], aA0, 4096); DSR(a0[3], aA0, 6144);
;   DSR(b1[0], aB1, 0); DSR(b1[1], aB1, 2048);
;   DSR(a1[0], aA1, 0); DSR(a1[1], aA1, 2048); DSR(a1[2], aA1, 4096); DSR(a1[3], aA1, 6144);
;   asm volatile("s_waitcnt lgkmcnt(6)" : "+v"(b0[0]), "+v"(b0[1]), "+v"(a0[0]), "+v"(a0[1]), "+v"(a0[2]), "+v"(a0[3]));
; #pragma unroll
;   for (int mi = 0; mi < 4; ++mi)
; #pragma unroll
;     for (int ni = 0; ni < 2; ++ni) {
;       if (VT) acc[mi][ni] = MFMA(a0[mi], b0[ni], acc[mi][ni]);
;       else acc[mi][ni] = MFMA(b0[ni], a0[mi], acc[mi][ni]);
;     }
;   __builtin_amdgcn_sched_barrier(0);
;   asm volatile("s_waitcnt lgkmcnt(0)" : "+v"(b1[0]), "+v"(b1[1]), "+v"(a1[0]), "+v"(a1[1]), "+v"(a1[2]), "+v"(a1[3]));
; #pragma unroll
;   for (int mi = 0; mi < 4; ++mi)
; #pragma unroll
;     for (int ni = 0; ni < 2; ++ni) {
;       if (VT) acc[mi][ni] = MFMA(a1[mi], b1[ni], acc[mi][ni]);
;       else acc[mi][ni] = MFMA(b1[ni], a1[mi], acc[mi][ni]);
;     }
; }
; template <bool VT>
; DI int gemm_kloop(const bf16_t* Ag, size_t lda, const bf16_t* Bg, size_t ldb, int nk, bf16_t* ring, f32x16 (&acc)[4][2], int tid, int wm, int wn,
;                   int r, int h, int st0, bool pre, const bf16_t* AgN, const bf16_t* BgN) {
;     ...
;   for (int kt = 0; kt < nk - 1; ++kt) {
;     asm volatile("s_waitcnt vmcnt(6)" ::: "memory");
;     __builtin_amdgcn_s_barrier();
;     if (kt + 2 < nk) dma_issue(Ag, lda, Bg, ldb, kt + 2, ring + (st == 0 ? 2 : st - 1) * STG, wid, lane);
;     const unsigned so = (unsigned)st * (unsigned)(STG * 2);
;     g_compute_asm<VT>(oA0 + so, oA1 + so, oB0 + so, oB1 + so, acc);
;     st = st == 2 ? 0 : st + 1;
;   }
;   asm volatile("s_waitcnt vmcnt(0)" ::: "memory");
;   __builtin_amdgcn_s_barrier();
;   if (AgN) {
;     const int s1 = st == 2 ? 0 : st + 1, s2 = s1 == 2 ? 0 : s1 + 1;
;     dma_issue(AgN, lda, BgN, ldb, 0, ring + s1 * STG, wid, lane);
;     dma_issue(AgN, lda, BgN, ldb, 1, ring + s2 * STG, wid, lane);
;   }
;   {
;     const unsigned so = (unsigned)st * (unsigned)(STG * 2);
;     g_compute_asm<VT>(oA0 + so, oA1 + so, oB0 + so, oB1 + so, acc);
	global_load_lds_dwordx4 v[166:167], off
	ds_read_b128 v[166:169], v174 offset:0
	ds_read_b128 v[170:173], v174 offset:2048
	ds_read_b128 v[174:177], v32 offset:0
	ds_read_b128 v[178:181], v32 offset:2048
	ds_read_b128 v[182:185], v32 offset:4096
	ds_read_b128 v[186:189], v32 offset:6144
	ds_read_b128 v[190:193], v198 offset:0
	ds_read_b128 v[194:197], v198 offset:2048
	ds_read_b128 v[198:201], v165 offset:0
	ds_read_b128 v[244:247], v165 offset:2048
	ds_read_b128 v[248:251], v165 offset:4096
	ds_read_b128 v[204:207], v165 offset:6144
	s_waitcnt lgkmcnt(9)
	v_mfma_f32_32x32x16_bf16 v[98:113], v[174:177], v[166:169], v[98:113]
	v_mfma_f32_32x32x16_bf16 v[114:129], v[174:177], v[170:173], v[114:129]
	s_add_u32 m0, s98, 0x1000
	v_lshl_add_u64 v[174:175], v[148:149], 0, s[40:41]
	global_load_lds_dwordx4 v[174:175], off
	s_waitcnt lgkmcnt(8)
	v_mfma_f32_32x32x16_bf16 v[66:81], v[178:181], v[166:169], v[66:81]
	v_mfma_f32_32x32x16_bf16 v[82:97], v[178:181], v[170:173], v[82:97]
	s_add_u32 m0, s98, 0x2000
	v_lshl_add_u64 v[174:175], v[146:147], 0, s[40:41]
	global_load_lds_dwordx4 v[174:175], off
	s_waitcnt lgkmcnt(7)
	v_mfma_f32_32x32x16_bf16 v[34:49], v[182:185], v[166:169], v[34:49]
	v_mfma_f32_32x32x16_bf16 v[50:65], v[182:185], v[170:173], v[50:65]
	s_add_u32 m0, s98, 0x3000
	v_lshl_add_u64 v[174:175], v[144:145], 0, s[40:41]
	global_load_lds_dwordx4 v[174:175], off
	s_waitcnt lgkmcnt(6)
	v_mfma_f32_32x32x16_bf16 v[0:15], v[186:189], v[166:169], v[0:15]
	v_mfma_f32_32x32x16_bf16 v[16:31], v[186:189], v[170:173], v[16:31]
	s_add_u32 m0, s98, 0x4000
	v_lshl_add_u64 v[174:175], v[142:143], 0, s[40:41]
	global_load_lds_dwordx4 v[174:175], off
	s_waitcnt lgkmcnt(3)
	v_mfma_f32_32x32x16_bf16 v[98:113], v[198:201], v[190:193], v[98:113]
	v_mfma_f32_32x32x16_bf16 v[114:129], v[198:201], v[194:197], v[114:129]
	s_add_u32 m0, s98, 0x5000
	v_lshl_add_u64 v[174:175], v[140:141], 0, s[40:41]
	global_load_lds_dwordx4 v[174:175], off
	s_add_i32 s42, s48, 1
	s_cmp_lg_u32 s48, 2
	s_cselect_b32 s48, s42, 0
	s_add_u32 s40, s40, 64
	s_addc_u32 s41, s41, 0
	s_cmpk_eq_i32 s40, 0x780
	s_waitcnt lgkmcnt(2)
	v_mfma_f32_32x32x16_bf16 v[66:81], v[244:247], v[190:193], v[66:81]
	v_mfma_f32_32x32x16_bf16 v[82:97], v[244:247], v[194:197], v[82:97]
	s_waitcnt lgkmcnt(1)
	v_mfma_f32_32x32x16_bf16 v[34:49], v[248:251], v[190:193], v[34:49]
	v_mfma_f32_32x32x16_bf16 v[50:65], v[248:251], v[194:197], v[50:65]
	s_waitcnt lgkmcnt(0)
	v_mfma_f32_32x32x16_bf16 v[0:15], v[204:207], v[190:193], v[0:15]
	v_mfma_f32_32x32x16_bf16 v[16:31], v[204:207], v[194:197], v[16:31]
	s_cbranch_scc0 .LBB0_655
	s_mul_i32 s40, s48, 0x6000
	v_add_u32_e32 v148, s40, v159
	s_waitcnt vmcnt(6)
	s_barrier
	v_add_u32_e32 v32, s40, v157
	v_add_u32_e32 v186, s40, v160
	ds_read_b128 v[140:143], v148 offset:0
	ds_read_b128 v[144:147], v148 offset:2048
	ds_read_b128 v[148:151], v32 offset:0
	ds_read_b128 v[166:169], v32 offset:2048
	ds_read_b128 v[170:173], v32 offset:4096
	ds_read_b128 v[174:177], v32 offset:6144
	v_add_u32_e32 v165, s40, v158
	ds_read_b128 v[178:181], v186 offset:0
	ds_read_b128 v[182:185], v186 offset:2048
	ds_read_b128 v[186:189], v165 offset:0
	ds_read_b128 v[190:193], v165 offset:2048
	ds_read_b128 v[194:197], v165 offset:4096
	ds_read_b128 v[198:201], v165 offset:6144
	s_waitcnt lgkmcnt(6)
	s_nop 0
	v_mfma_f32_32x32x16_bf16 v[98:113], v[148:151], v[140:143], v[98:113]
	v_mfma_f32_32x32x16_bf16 v[114:129], v[148:151], v[144:147], v[114:129]
	v_mfma_f32_32x32x16_bf16 v[66:81], v[166:169], v[140:143], v[66:81]
	v_mfma_f32_32x32x16_bf16 v[82:97], v[166:169], v[144:147], v[82:97]
	v_mfma_f32_32x32x16_bf16 v[34:49], v[170:173], v[140:143], v[34:49]
	v_mfma_f32_32x32x16_bf16 v[50:65], v[170:173], v[144:147], v[50:65]
	v_mfma_f32_32x32x16_bf16 v[0:15], v[174:177], v[140:143], v[0:15]
	v_mfma_f32_32x32x16_bf16 v[16:31], v[174:177], v[144:147], v[16:31]
	s_waitcnt lgkmcnt(0)
	s_add_i32 s40, s48, 1
	v_mfma_f32_32x32x16_bf16 v[98:113], v[186:189], v[178:181], v[98:113]
	s_waitcnt vmcnt(0)
	s_cmp_lg_u32 s48, 2
	s_cselect_b32 s67, s40, 0
	s_cmp_lg_u64 s[36:37], 0
	s_barrier
; DI void dma_issue(const bf16_t* Ag, size_t lda, const bf16_t* Bg, size_t ldb, int kt, bf16_t* stage, int wid, int lane) {
;   const int rl = lane >> 2, c = (lane & 3) ^ ((lane >> 4) & 3);
; #pragma unroll
;   for (int i = 0; i < 4; ++i) {
;     const int j = wid + 4 * i;
;     __builtin_amdgcn_global_load_lds((const unsigned*)(Ag + (size_t)(16 * j + rl) * lda + kt * 32 + c * 8), (unsigned*)(stage + j * 512), 16, 0, 0);
;   }
; #pragma unroll
;   for (int i = 0; i < 2; ++i) {
;     const int j = wid + 4 * i;
;     __builtin_amdgcn_global_load_lds((const unsigned*)(Bg + (size_t)(16 * j + rl) * ldb + kt * 32 + c * 8), (unsigned*)(stage + STG_A + j * 512), 16, 0, 0);
;   }
; }
; template <bool VT>
; DI int gemm_kloop(const bf16_t* Ag, size_t lda, const bf16_t* Bg, size_t ldb, int nk, bf16_t* ring, f32x16 (&acc)[4][2], int tid, int wm, int wn,
;                   int r, int h, int st0, bool pre, const bf16_t* AgN, const bf16_t* BgN) {
;     ...
;   if (AgN) {
;     const int s1 = st == 2 ? 0 : st + 1, s2 = s1 == 2 ? 0 : s1 + 1;
;     dma_issue(AgN, lda, BgN, ldb, 0, ring + s1 * STG, wid, lane);
;     dma_issue(AgN, lda, BgN, ldb, 1, ring + s2 * STG, wid, lane);
;   }
;   {
;     const unsigned so = (unsigned)st * (unsigned)(STG * 2);
;     g_compute_asm<VT>(oA0 + so, oA1 + so, oB0 + so, oB1 + so, acc);
	v_mfma_f32_32x32x16_bf16 v[114:129], v[186:189], v[182:185], v[114:129]
	v_mfma_f32_32x32x16_bf16 v[66:81], v[190:193], v[178:181], v[66:81]
	v_mfma_f32_32x32x16_bf16 v[82:97], v[190:193], v[182:185], v[82:97]
	v_mfma_f32_32x32x16_bf16 v[34:49], v[194:197], v[178:181], v[34:49]
	v_mfma_f32_32x32x16_bf16 v[50:65], v[194:197], v[182:185], v[50:65]
	v_mfma_f32_32x32x16_bf16 v[0:15], v[198:201], v[178:181], v[0:15]
	v_mfma_f32_32x32x16_bf16 v[16:31], v[198:201], v[182:185], v[16:31]
	s_cbranch_scc0 .LBB0_658
	s_add_i32 s40, s67, 1
	s_cmp_lg_u32 s67, 2
	s_cselect_b32 s40, s40, 0
	s_mul_i32 s41, s40, 0x3000
	s_lshl_b32 s42, s41, 1
	v_lshlrev_b32_e32 v32, 1, v162
	v_add_u32_e32 v146, s42, v32
	v_lshlrev_b32_e32 v147, 1, v161
	v_lshl_add_u64 v[140:141], s[36:37], 0, v[138:139]
	v_lshlrev_b64 v[130:131], 1, v[130:131]
	v_readfirstlane_b32 s36, v146
	v_add_u32_e32 v148, s42, v147
	v_lshl_add_u64 v[142:143], v[140:141], 0, v[130:131]
	s_mov_b32 m0, s36
	v_lshlrev_b64 v[132:133], 1, v[132:133]
	v_readfirstlane_b32 s36, v148
	v_add_u32_e32 v149, s42, v164
	global_load_lds_dwordx4 v[142:143], off
	v_lshl_add_u64 v[144:145], v[140:141], 0, v[132:133]
	s_mov_b32 m0, s36
	v_lshl_add_u64 v[134:135], v[134:135], 1, v[140:141]
	v_readfirstlane_b32 s36, v149
	v_lshl_add_u64 v[136:137], v[136:137], 1, v[140:141]
	v_add_u32_e32 v140, s42, v163
	global_load_lds_dwordx4 v[144:145], off
	s_mov_b32 m0, s36
	v_readfirstlane_b32 s36, v140
	v_lshl_add_u64 v[138:139], s[38:39], 0, v[138:139]
	v_add_u32_e32 v140, 0x4000, v146
	global_load_lds_dwordx4 v[134:135], off
	s_mov_b32 m0, s36
	v_lshl_add_u64 v[130:131], v[138:139], 0, v[130:131]
	v_readfirstlane_b32 s36, v140
	v_lshl_add_u64 v[132:133], v[138:139], 0, v[132:133]
	v_add_u32_e32 v138, 0x4000, v148
	s_addk_i32 s41, 0x3000
	global_load_lds_dwordx4 v[136:137], off
	s_mov_b32 m0, s36
	v_readfirstlane_b32 s36, v138
	s_cmp_lg_u32 s40, 2
	global_load_lds_dwordx4 v[130:131], off
	s_mov_b32 m0, s36
	s_cselect_b32 s36, s41, 0
	s_lshl_b32 s36, s36, 1
	v_add_u32_e32 v32, s36, v32
	v_add_u32_e32 v140, s36, v147
	v_readfirstlane_b32 s37, v32
	global_load_lds_dwordx4 v[132:133], off
	v_lshl_add_u64 v[138:139], v[142:143], 0, 64
	s_mov_b32 m0, s37
	v_readfirstlane_b32 s37, v140
	global_load_lds_dwordx4 v[138:139], off
	v_lshl_add_u64 v[138:139], v[144:145], 0, 64
	s_mov_b32 m0, s37
	v_lshl_add_u64 v[134:135], v[134:135], 0, 64
	global_load_lds_dwordx4 v[138:139], off
	v_add_u32_e32 v138, s36, v164
	v_add_u32_e32 v32, 0x4000, v32
	v_readfirstlane_b32 s37, v138
	s_mov_b32 m0, s37
	v_lshl_add_u64 v[130:131], v[130:131], 0, 64
	global_load_lds_dwordx4 v[134:135], off
	v_lshl_add_u64 v[134:135], v[136:137], 0, 64
	v_add_u32_e32 v136, s36, v163
	s_nop 0
	v_readfirstlane_b32 s36, v136
	s_mov_b32 m0, s36
	v_readfirstlane_b32 s36, v32
	v_add_u32_e32 v32, 0x4000, v140
	global_load_lds_dwordx4 v[134:135], off
	s_mov_b32 m0, s36
	v_readfirstlane_b32 s36, v32
	global_load_lds_dwordx4 v[130:131], off
	v_lshl_add_u64 v[130:131], v[132:133], 0, 64
	s_mov_b32 m0, s36
	s_nop 0
	global_load_lds_dwordx4 v[130:131], off
